# adds: nt on X16 epilogue loads and stores in P6 and P9
# speedup vs baseline: 1.0202x; 1.0043x over previous
;     __device__ __forceinline__ void operator()(const f32x4 (&acc)[2][2][4][2], const Unit& u, int wr, int wc, int fr, int fq) const {
;     ...
;         if constexpr (GN) { ssq_t sc_[8];
; #pragma unroll
;             for (int i = 0; i < 8; ++i) sc_[i] = gsc[u.pm * BM + wr * 64 + fr + (i >> 2) * HALF + (i & 3) * 16];
; #pragma unroll
;             for (int i = 0; i < 8; ++i) rc[i] = 1.0f / sqrtf(ssq_val(sc_[i]) * (1.0f / 256.0f) + EPS); }
;         const int col0 = u.pn * BM + wc * 32 + 8 * fq; const int b = (u.pm * BM) >> 12;
;         const float* gp = gate + (size_t)b * NMOD + col0; const float* sp = sc + (size_t)b * NMOD + col0;
;         f32x4 g[2][2], cf[2][2];
; #pragma unroll
;         for (int bj = 0; bj < 2; ++bj) {
;             g[bj][0] = *(const f32x4*)(gp + bj * HALF); g[bj][1] = *(const f32x4*)(gp + bj * HALF + 4);
;             const f32x4 n0 = *(const f32x4*)(nw + col0 + bj * HALF), n1 = *(const f32x4*)(nw + col0 + bj * HALF + 4);
;             const f32x4 c0 = *(const f32x4*)(sp + bj * HALF), c1 = *(const f32x4*)(sp + bj * HALF + 4);
;             cf[bj][0] = n0 * (c0 + 1.0f); cf[bj][1] = n1 * (c1 + 1.0f);
;         }
; #pragma unroll
;         for (int ai = 0; ai < 2; ++ai)
; #pragma unroll
;         for (int mp = 0; mp < 4; mp += 2) {
;             u32x4 bv[2][2];
; #pragma unroll
;             for (int mm = 0; mm < 2; ++mm)
; #pragma unroll
;                 for (int bj = 0; bj < 2; ++bj)
;                     bv[mm][bj] = *(gl_u32x4*)(PG8_GCPTR(base) + (unsigned)((u.pm * BM + ai * HALF + wr * 64 + (mp + mm) * 16 + fr) * DM + col0 + bj * HALF) * 2u);
; #pragma unroll
;             for (int mm = 0; mm < 2; ++mm) {
;                 const int m = mp + mm;
;                 const int row = u.pm * BM + ai * HALF + wr * 64 + m * 16 + fr; float q = 0.f;
; #pragma unroll
;                 for (int bj = 0; bj < 2; ++bj) {
;                     const unsigned offb = (unsigned)(row * DM + col0 + bj * HALF) * 2u;
;                     const u32x4 bw = bv[mm][bj];
;                     const f32x4 b0 = (f32x4){__uint_as_float(bw.x << 16), __uint_as_float(bw.x & 0xffff0000u), __uint_as_float(bw.y << 16), __uint_as_float(bw.y & 0xffff0000u)};
;                     const f32x4 b1 = (f32x4){__uint_as_float(bw.z << 16), __uint_as_float(bw.z & 0xffff0000u), __uint_as_float(bw.w << 16), __uint_as_float(bw.w & 0xffff0000u)};
.LBB0_1087:
	s_lshl_b32 s2, s10, 8
	v_mbcnt_lo_u32_b32 v0, -1, 0
	v_mbcnt_hi_u32_b32 v0, -1, v0
	s_add_i32 s2, s2, s90
	v_and_b32_e32 v182, 15, v0
	v_or_b32_e32 v216, s2, v182
	v_ashrrev_i32_e32 v217, 31, v216
	v_lshl_add_u64 v[2:3], v[216:217], 3, s[16:17]
	global_load_dwordx2 v[70:71], v[2:3], off
	global_load_dwordx2 v[218:219], v[2:3], off offset:128
	global_load_dwordx2 v[214:215], v[2:3], off offset:256
	global_load_dwordx2 v[212:213], v[2:3], off offset:384
	global_load_dwordx2 v[210:211], v[2:3], off offset:1024
	global_load_dwordx2 v[208:209], v[2:3], off offset:1152
	global_load_dwordx2 v[206:207], v[2:3], off offset:1280
	s_nop 0
	global_load_dwordx2 v[2:3], v[2:3], off offset:1408
	v_bfe_u32 v183, v0, 4, 2
	v_lshlrev_b32_e32 v232, 11, v216
	s_waitcnt vmcnt(0) lgkmcnt(0)
	v_ffbh_u32_e32 v0, v71
	v_min_u32_e32 v0, 32, v0
	v_lshlrev_b64 v[70:71], v0, v[70:71]
	v_min_u32_e32 v70, 1, v70
	v_or_b32_e32 v70, v71, v70
	v_cvt_f32_u32_e32 v70, v70
	v_sub_u32_e32 v0, 32, v0
	v_ldexp_f32 v0, v70, v0
	v_mul_f32_e32 v0, 0x33800000, v0
	v_fmamk_f32 v0, v0, 0x3b800000, v226
	v_cmp_eq_u32_e64 s[8:9], 0, v183
	s_nop 0
	s_lshl_b32 s2, s50, 8
	v_rsq_f32_e32 v0, v0
	s_nop 0
	v_lshl_or_b32 v70, v183, 3, s2
	s_ashr_i32 s2, s10, 4
	v_or_b32_e32 v180, s91, v70
	s_mul_i32 s5, s2, 0x6000
	s_mul_hi_i32 s4, s2, 0x6000
	s_add_u32 s2, s52, s5
	v_ashrrev_i32_e32 v181, 31, v180
	s_addc_u32 s3, s83, s4
	v_lshlrev_b64 v[70:71], 2, v[180:181]
	v_lshl_add_u64 v[158:159], s[2:3], 0, v[70:71]
	s_add_u32 s2, s88, s5
	s_addc_u32 s3, s89, s4
	v_lshl_add_u64 v[174:175], s[2:3], 0, v[70:71]
	v_lshl_add_u64 v[160:161], s[20:21], 0, v[70:71]
	global_load_dwordx4 v[82:85], v[158:159], off
	global_load_dwordx4 v[78:81], v[158:159], off offset:16
	global_load_dwordx4 v[70:73], v[160:161], off offset:16
	global_load_dwordx4 v[74:77], v[160:161], off
	global_load_dwordx4 v[150:153], v[174:175], off
	global_load_dwordx4 v[154:157], v[174:175], off offset:16
	v_lshlrev_b32_e32 v230, 1, v180
	v_add_u32_e32 v231, v230, v232
	v_and_b32_e32 v240, 0xffff8000, v231
	v_bfe_u32 v241, v231, 11, 4
	v_lshl_or_b32 v240, v241, 6, v240
	v_bfe_u32 v241, v231, 9, 2
	v_lshl_or_b32 v240, v241, 13, v240
	v_bfe_u32 v241, v231, 6, 2
	v_lshl_or_b32 v240, v241, 11, v240
	v_and_b32_e32 v241, 48, v231
	v_or_b32_e32 v240, v240, v241
	s_movk_i32 s2, 0x80
	v_pk_mul_f32 v[146:147], v[146:147], v[0:1] op_sel_hi:[1,0]
	v_pk_mul_f32 v[148:149], v[148:149], v[0:1] op_sel_hi:[1,0]
	v_pk_mul_f32 v[142:143], v[142:143], v[0:1] op_sel_hi:[1,0]
	v_pk_mul_f32 v[144:145], v[144:145], v[0:1] op_sel_hi:[1,0]
	v_pk_mul_f32 v[138:139], v[138:139], v[0:1] op_sel_hi:[1,0]
	v_pk_mul_f32 v[140:141], v[140:141], v[0:1] op_sel_hi:[1,0]
	v_pk_mul_f32 v[134:135], v[134:135], v[0:1] op_sel_hi:[1,0]
	v_pk_mul_f32 v[136:137], v[136:137], v[0:1] op_sel_hi:[1,0]
	s_waitcnt vmcnt(0) lgkmcnt(0)
	v_pk_add_f32 v[152:153], v[152:153], 1.0 op_sel_hi:[1,0]
	v_pk_add_f32 v[150:151], v[150:151], 1.0 op_sel_hi:[1,0]
	v_pk_mul_f32 v[200:201], v[76:77], v[152:153]
	v_pk_mul_f32 v[204:205], v[74:75], v[150:151]
	v_pk_add_f32 v[74:75], v[156:157], 1.0 op_sel_hi:[1,0]
	v_pk_add_f32 v[76:77], v[154:155], 1.0 op_sel_hi:[1,0]
	v_pk_mul_f32 v[198:199], v[72:73], v[74:75]
	v_pk_mul_f32 v[202:203], v[70:71], v[76:77]
	global_load_dwordx4 v[74:77], v[158:159], off offset:512
	global_load_dwordx4 v[70:73], v[158:159], off offset:528
	global_load_dwordx4 v[150:153], v[160:161], off offset:528
	global_load_dwordx4 v[154:157], v[160:161], off offset:512
	s_nop 0
	global_load_dwordx4 v[158:161], v[174:175], off offset:512
	global_load_dwordx4 v[176:179], v[174:175], off offset:528
	s_waitcnt vmcnt(0) lgkmcnt(0)
	v_pk_add_f32 v[160:161], v[160:161], 1.0 op_sel_hi:[1,0]
	v_pk_add_f32 v[158:159], v[158:159], 1.0 op_sel_hi:[1,0]
	v_pk_mul_f32 v[196:197], v[156:157], v[160:161]
	v_pk_mul_f32 v[174:175], v[154:155], v[158:159]
	v_pk_add_f32 v[154:155], v[178:179], 1.0 op_sel_hi:[1,0]
	global_load_dwordx4 v[178:181], v240, s[22:23] nt
	global_load_dwordx4 v[158:161], v240, s[22:23] offset:1024 nt
	v_pk_add_f32 v[156:157], v[176:177], 1.0 op_sel_hi:[1,0]
	v_pk_mul_f32 v[176:177], v[152:153], v[154:155]
	v_pk_mul_f32 v[194:195], v[150:151], v[156:157]
	v_lshlrev_b32_e32 v150, 6, v183
	v_lshlrev_b32_e32 v151, 2, v182
	v_bitop3_b32 v229, v150, 64, v151 bitop3:0x36
	v_bitop3_b32 v228, v150, s2, v151 bitop3:0x36
	v_add_u32_e32 v150, 0x8000, v240
	global_load_dwordx4 v[154:157], v150, s[22:23] nt
	s_nop 0
	global_load_dwordx4 v[150:153], v150, s[22:23] offset:1024 nt
	s_waitcnt vmcnt(3)
	v_lshlrev_b32_e32 v182, 16, v178
	v_and_b32_e32 v183, 0xffff0000, v178
	v_lshlrev_b32_e32 v178, 16, v179
	v_and_b32_e32 v179, 0xffff0000, v179
	v_lshlrev_b32_e32 v184, 16, v180
	v_and_b32_e32 v185, 0xffff0000, v180
	v_lshlrev_b32_e32 v180, 16, v181
	v_and_b32_e32 v181, 0xffff0000, v181
	v_pk_fma_f32 v[148:149], v[84:85], v[148:149], v[178:179]
	v_pk_fma_f32 v[146:147], v[82:83], v[146:147], v[182:183]
	v_pk_fma_f32 v[178:179], v[80:81], v[144:145], v[180:181]
	v_pk_fma_f32 v[180:181], v[78:79], v[142:143], v[184:185]
	v_cvt_pk_bf16_f32 v142, v146, v147
	v_cvt_pk_bf16_f32 v143, v148, v149
	v_pk_mul_f32 v[182:183], v[198:199], v[178:179]
	v_cvt_pk_bf16_f32 v144, v180, v181
	v_cvt_pk_bf16_f32 v145, v178, v179
	global_store_dwordx4 v240, v[142:145], s[24:25] nt
	v_pk_mul_f32 v[184:185], v[202:203], v[180:181]
	s_nop 0
	v_pk_mul_f32 v[142:143], v[204:205], v[146:147]
	v_pk_mul_f32 v[144:145], v[200:201], v[148:149]
	v_cvt_pk_bf16_f32 v142, v142, v143
	s_nop 0
	v_cvt_pk_bf16_f32 v143, v144, v145
	v_cvt_pk_bf16_f32 v144, v184, v185
	v_cvt_pk_bf16_f32 v145, v182, v183
	global_store_dwordx4 v231, v[142:145], s[26:27]
	s_nop 1
	v_mul_f32_e32 v142, v147, v147
	v_mul_f32_e32 v143, v149, v149
	v_fmac_f32_e32 v142, v146, v146
	v_fmac_f32_e32 v143, v148, v148
	v_add_f32_e32 v142, v142, v143
	v_mul_f32_e32 v143, v181, v181
	v_fmac_f32_e32 v143, v180, v180
	v_add_f32_e32 v142, v143, v142
	v_mul_f32_e32 v143, v179, v179
	v_fmac_f32_e32 v143, v178, v178
	v_add_f32_e32 v178, v143, v142
	s_waitcnt vmcnt(4)
; __device__ __forceinline__ unsigned cvt_pk_bf16(float lo, float hi) { unsigned r; asm volatile("v_cvt_pk_bf16_f32 %0, %1, %2" : "=v"(r) : "v"(lo), "v"(hi)); return r; }
; #define PG8_GPTR(p) ((__attribute__((address_space(1))) char*)(p))
;     __device__ __forceinline__ void operator()(const f32x4 (&acc)[2][2][4][2], const Unit& u, int wr, int wc, int fr, int fq) const {
;     ...
;                     bv[mm][bj] = *(gl_u32x4*)(PG8_GCPTR(base) + (unsigned)((u.pm * BM + ai * HALF + wr * 64 + (mp + mm) * 16 + fr) * DM + col0 + bj * HALF) * 2u);
; #pragma unroll
;             for (int mm = 0; mm < 2; ++mm) {
;                 const int m = mp + mm;
;                 const int row = u.pm * BM + ai * HALF + wr * 64 + m * 16 + fr; float q = 0.f;
; #pragma unroll
;                 for (int bj = 0; bj < 2; ++bj) {
;                     const unsigned offb = (unsigned)(row * DM + col0 + bj * HALF) * 2u;
;                     const u32x4 bw = bv[mm][bj];
;                     const f32x4 b0 = (f32x4){__uint_as_float(bw.x << 16), __uint_as_float(bw.x & 0xffff0000u), __uint_as_float(bw.y << 16), __uint_as_float(bw.y & 0xffff0000u)};
;                     const f32x4 b1 = (f32x4){__uint_as_float(bw.z << 16), __uint_as_float(bw.z & 0xffff0000u), __uint_as_float(bw.w << 16), __uint_as_float(bw.w & 0xffff0000u)};
;                     f32x4 a0 = acc[ai][bj][m][0], a1 = acc[ai][bj][m][1]; if constexpr (GN) { a0 *= rc[ai * 4 + m]; a1 *= rc[ai * 4 + m]; }
;                     const f32x4 o0 = b0 + g[bj][0] * a0, o1 = b1 + g[bj][1] * a1;
;                     u32x4 wo; wo.x = cvt_pk_bf16(o0[0], o0[1]); wo.y = cvt_pk_bf16(o0[2], o0[3]); wo.z = cvt_pk_bf16(o1[0], o1[1]); wo.w = cvt_pk_bf16(o1[2], o1[3]);
;                     *(gs_u32x4*)(PG8_GPTR(out) + offb) = wo;
;                     if (xg) {
;                         const f32x4 h0 = o0 * cf[bj][0], h1 = o1 * cf[bj][1];
;                         u32x4 w; w.x = cvt_pk_bf16(h0[0], h0[1]); w.y = cvt_pk_bf16(h0[2], h0[3]); w.z = cvt_pk_bf16(h1[0], h1[1]); w.w = cvt_pk_bf16(h1[2], h1[3]);
;                         *(gs_u32x4*)(PG8_GPTR(xg) + offb) = w;
;                         q += (o0[0] * o0[0] + o0[1] * o0[1]) + (o0[2] * o0[2] + o0[3] * o0[3]) + (o1[0] * o1[0] + o1[1] * o1[1]) + (o1[2] * o1[2] + o1[3] * o1[3]);
;                     }
;                 }
;                 if (xg) ssq_put(ssq, row, q, fr, fq);
;             }
	v_lshlrev_b32_e32 v142, 16, v158
	v_and_b32_e32 v143, 0xffff0000, v158
	v_lshlrev_b32_e32 v144, 16, v159
	v_and_b32_e32 v145, 0xffff0000, v159
	v_lshlrev_b32_e32 v146, 16, v160
	v_and_b32_e32 v147, 0xffff0000, v160
	v_lshlrev_b32_e32 v148, 16, v161
	v_and_b32_e32 v149, 0xffff0000, v161
	v_pk_fma_f32 v[140:141], v[140:141], v[76:77], v[144:145]
	v_pk_fma_f32 v[138:139], v[138:139], v[74:75], v[142:143]
	v_pk_fma_f32 v[142:143], v[136:137], v[72:73], v[148:149]
	v_pk_fma_f32 v[144:145], v[134:135], v[70:71], v[146:147]
	v_cvt_pk_bf16_f32 v134, v138, v139
	v_cvt_pk_bf16_f32 v135, v140, v141
	v_pk_mul_f32 v[146:147], v[176:177], v[142:143]
	v_cvt_pk_bf16_f32 v136, v144, v145
	v_cvt_pk_bf16_f32 v137, v142, v143
	global_store_dwordx4 v240, v[134:137], s[24:25] offset:1024 nt
	v_pk_mul_f32 v[148:149], v[194:195], v[144:145]
	v_mul_f32_e32 v0, v143, v143
	v_pk_mul_f32 v[136:137], v[196:197], v[140:141]
	v_pk_mul_f32 v[134:135], v[174:175], v[138:139]
	v_fmac_f32_e32 v0, v142, v142
	v_cvt_pk_bf16_f32 v134, v134, v135
	v_cvt_pk_bf16_f32 v135, v136, v137
	v_cvt_pk_bf16_f32 v136, v148, v149
	v_cvt_pk_bf16_f32 v137, v146, v147
	global_store_dwordx4 v231, v[134:137], s[26:27] offset:256
	s_nop 1
	v_mul_f32_e32 v135, v139, v139
	v_mul_f32_e32 v136, v141, v141
	v_mul_f32_e32 v134, v145, v145
	v_fmac_f32_e32 v135, v138, v138
	v_fmac_f32_e32 v136, v140, v140
	v_fmac_f32_e32 v134, v144, v144
	v_add_f32_e32 v135, v135, v136
	v_add_f32_e32 v134, v134, v135
	v_add_f32_e32 v0, v0, v134
	v_add_f32_e32 v0, v178, v0
	ds_bpermute_b32 v134, v229, v0
	s_waitcnt lgkmcnt(0)
	v_add_f32_e32 v0, v0, v134
	ds_bpermute_b32 v136, v228, v0
	v_lshl_add_u64 v[134:135], v[216:217], 3, s[28:29]
	s_and_saveexec_b64 s[2:3], s[8:9]
	s_cbranch_execz .LBB0_1089
	s_waitcnt lgkmcnt(0)
	v_add_f32_e32 v0, v0, v136
	v_mul_f32_e32 v0, 0x4b800000, v0
	v_trunc_f32_e32 v0, v0
	v_mul_f32_e32 v136, 0x2f800000, v0
	v_floor_f32_e32 v137, v136
	v_fmac_f32_e32 v0, 0xcf800000, v137
	v_cvt_u32_f32_e32 v136, v0
	v_cvt_u32_f32_e32 v137, v137
	global_atomic_add_x2 v[134:135], v[136:137], off
.LBB0_1089:
	s_or_b64 exec, exec, s[2:3]
	v_ffbh_u32_e32 v0, v219
	v_min_u32_e32 v0, 32, v0
	s_waitcnt lgkmcnt(0)
	v_lshlrev_b64 v[136:137], v0, v[218:219]
	v_min_u32_e32 v136, 1, v136
	v_or_b32_e32 v136, v137, v136
	v_cvt_f32_u32_e32 v136, v136
	v_sub_u32_e32 v0, 32, v0
	s_waitcnt vmcnt(0)
	v_and_b32_e32 v141, 0xffff0000, v155
	v_lshlrev_b32_e32 v142, 16, v156
	v_ldexp_f32 v0, v136, v0
	v_mul_f32_e32 v0, 0x33800000, v0
	v_fmamk_f32 v0, v0, 0x3b800000, v226
	v_and_b32_e32 v143, 0xffff0000, v156
	v_lshlrev_b32_e32 v144, 16, v157
	v_and_b32_e32 v145, 0xffff0000, v157
	s_mov_b32 s2, 0x8000
	v_rsq_f32_e32 v0, v0
	s_nop 0
	v_lshlrev_b32_e32 v136, 11, v216
	v_lshlrev_b32_e32 v138, 16, v154
	v_and_b32_e32 v139, 0xffff0000, v154
	v_lshlrev_b32_e32 v140, 16, v155
	v_pk_mul_f32 v[130:131], v[130:131], v[0:1] op_sel_hi:[1,0]
	v_pk_mul_f32 v[132:133], v[132:133], v[0:1] op_sel_hi:[1,0]
	v_pk_mul_f32 v[126:127], v[126:127], v[0:1] op_sel_hi:[1,0]
	v_add3_u32 v137, v230, v136, s2
	v_add_u32_e32 v241, s2, v240
	v_pk_mul_f32 v[128:129], v[128:129], v[0:1] op_sel_hi:[1,0]
	v_pk_fma_f32 v[132:133], v[84:85], v[132:133], v[140:141]
	v_pk_fma_f32 v[130:131], v[82:83], v[130:131], v[138:139]
	v_pk_fma_f32 v[140:141], v[78:79], v[126:127], v[142:143]
	v_cvt_pk_bf16_f32 v126, v130, v131
	v_cvt_pk_bf16_f32 v127, v132, v133
	v_pk_fma_f32 v[138:139], v[80:81], v[128:129], v[144:145]
	v_cvt_pk_bf16_f32 v128, v140, v141
	v_pk_mul_f32 v[144:145], v[202:203], v[140:141]
	v_cvt_pk_bf16_f32 v129, v138, v139
	global_store_dwordx4 v241, v[126:129], s[24:25] nt
	v_pk_mul_f32 v[142:143], v[198:199], v[138:139]
	v_pk_mul_f32 v[122:123], v[122:123], v[0:1] op_sel_hi:[1,0]
	v_pk_mul_f32 v[126:127], v[204:205], v[130:131]
	v_pk_mul_f32 v[128:129], v[200:201], v[132:133]
	v_cvt_pk_bf16_f32 v126, v126, v127
	v_pk_mul_f32 v[124:125], v[124:125], v[0:1] op_sel_hi:[1,0]
	v_cvt_pk_bf16_f32 v127, v128, v129
	v_cvt_pk_bf16_f32 v128, v144, v145
	v_cvt_pk_bf16_f32 v129, v142, v143
	global_store_dwordx4 v137, v[126:129], s[26:27]
	v_pk_mul_f32 v[118:119], v[118:119], v[0:1] op_sel_hi:[1,0]
	v_pk_mul_f32 v[120:121], v[120:121], v[0:1] op_sel_hi:[1,0]
	v_mul_f32_e32 v126, v131, v131
	v_mul_f32_e32 v127, v133, v133
	v_fmac_f32_e32 v126, v130, v130
	v_fmac_f32_e32 v127, v132, v132
	v_add_f32_e32 v126, v126, v127
	v_mul_f32_e32 v127, v141, v141
	v_fmac_f32_e32 v127, v140, v140
	v_add_f32_e32 v126, v127, v126
	v_mul_f32_e32 v127, v139, v139
	v_fmac_f32_e32 v127, v138, v138
	v_add_f32_e32 v138, v127, v126
	v_lshlrev_b32_e32 v126, 16, v150
	v_and_b32_e32 v127, 0xffff0000, v150
	v_lshlrev_b32_e32 v128, 16, v151
	v_and_b32_e32 v129, 0xffff0000, v151
	v_lshlrev_b32_e32 v130, 16, v152
	v_and_b32_e32 v131, 0xffff0000, v152
	v_lshlrev_b32_e32 v132, 16, v153
	v_and_b32_e32 v133, 0xffff0000, v153
	v_pk_fma_f32 v[124:125], v[124:125], v[76:77], v[128:129]
	v_pk_fma_f32 v[122:123], v[122:123], v[74:75], v[126:127]
	v_pk_fma_f32 v[126:127], v[120:121], v[72:73], v[132:133]
	v_pk_fma_f32 v[128:129], v[118:119], v[70:71], v[130:131]
	v_cvt_pk_bf16_f32 v118, v122, v123
	v_cvt_pk_bf16_f32 v119, v124, v125
	v_mul_f32_e32 v0, v127, v127
	v_cvt_pk_bf16_f32 v120, v128, v129
	v_cvt_pk_bf16_f32 v121, v126, v127
	global_store_dwordx4 v241, v[118:121], s[24:25] offset:1024 nt
	v_fmac_f32_e32 v0, v126, v126
	v_pk_mul_f32 v[130:131], v[196:197], v[124:125]
	v_mul_f32_e32 v119, v123, v123
	v_mul_f32_e32 v120, v125, v125
	v_mul_f32_e32 v118, v129, v129
	v_fmac_f32_e32 v119, v122, v122
	v_fmac_f32_e32 v120, v124, v124
	v_fmac_f32_e32 v118, v128, v128
	v_add_f32_e32 v119, v119, v120
	v_add_f32_e32 v118, v118, v119
	v_add_f32_e32 v0, v0, v118
	v_add_f32_e32 v0, v138, v0
	ds_bpermute_b32 v121, v229, v0
	v_pk_mul_f32 v[118:119], v[174:175], v[122:123]
	v_pk_mul_f32 v[122:123], v[194:195], v[128:129]
	v_cvt_pk_bf16_f32 v120, v118, v119
	v_pk_mul_f32 v[124:125], v[176:177], v[126:127]
	s_waitcnt lgkmcnt(0)
	v_add_f32_e32 v0, v0, v121
	ds_bpermute_b32 v118, v228, v0
	v_cvt_pk_bf16_f32 v121, v130, v131
	v_cvt_pk_bf16_f32 v122, v122, v123
	v_cvt_pk_bf16_f32 v123, v124, v125
	global_store_dwordx4 v137, v[120:123], s[26:27] offset:256
	s_and_saveexec_b64 s[2:3], s[8:9]
	s_cbranch_execz .LBB0_1091
	s_waitcnt lgkmcnt(0)
	v_add_f32_e32 v0, v0, v118
	v_mul_f32_e32 v0, 0x4b800000, v0
	v_trunc_f32_e32 v0, v0
	v_mul_f32_e32 v118, 0x2f800000, v0
	v_floor_f32_e32 v119, v118
	v_fmac_f32_e32 v0, 0xcf800000, v119
	v_cvt_u32_f32_e32 v118, v0
	v_cvt_u32_f32_e32 v119, v119
	global_atomic_add_x2 v[134:135], v[118:119], off offset:128
; __device__ __forceinline__ unsigned cvt_pk_bf16(float lo, float hi) { unsigned r; asm volatile("v_cvt_pk_bf16_f32 %0, %1, %2" : "=v"(r) : "v"(lo), "v"(hi)); return r; }
; #define PG8_GPTR(p) ((__attribute__((address_space(1))) char*)(p))
;     __device__ __forceinline__ void operator()(const f32x4 (&acc)[2][2][4][2], const Unit& u, int wr, int wc, int fr, int fq) const {
;     ...
;                     bv[mm][bj] = *(gl_u32x4*)(PG8_GCPTR(base) + (unsigned)((u.pm * BM + ai * HALF + wr * 64 + (mp + mm) * 16 + fr) * DM + col0 + bj * HALF) * 2u);
; #pragma unroll
;             for (int mm = 0; mm < 2; ++mm) {
;                 const int m = mp + mm;
;                 const int row = u.pm * BM + ai * HALF + wr * 64 + m * 16 + fr; float q = 0.f;
; #pragma unroll
;                 for (int bj = 0; bj < 2; ++bj) {
;                     const unsigned offb = (unsigned)(row * DM + col0 + bj * HALF) * 2u;
;                     const u32x4 bw = bv[mm][bj];
;                     const f32x4 b0 = (f32x4){__uint_as_float(bw.x << 16), __uint_as_float(bw.x & 0xffff0000u), __uint_as_float(bw.y << 16), __uint_as_float(bw.y & 0xffff0000u)};
;                     const f32x4 b1 = (f32x4){__uint_as_float(bw.z << 16), __uint_as_float(bw.z & 0xffff0000u), __uint_as_float(bw.w << 16), __uint_as_float(bw.w & 0xffff0000u)};
;                     f32x4 a0 = acc[ai][bj][m][0], a1 = acc[ai][bj][m][1]; if constexpr (GN) { a0 *= rc[ai * 4 + m]; a1 *= rc[ai * 4 + m]; }
;                     const f32x4 o0 = b0 + g[bj][0] * a0, o1 = b1 + g[bj][1] * a1;
;                     u32x4 wo; wo.x = cvt_pk_bf16(o0[0], o0[1]); wo.y = cvt_pk_bf16(o0[2], o0[3]); wo.z = cvt_pk_bf16(o1[0], o1[1]); wo.w = cvt_pk_bf16(o1[2], o1[3]);
;                     *(gs_u32x4*)(PG8_GPTR(out) + offb) = wo;
;                     if (xg) {
;                         const f32x4 h0 = o0 * cf[bj][0], h1 = o1 * cf[bj][1];
;                         u32x4 w; w.x = cvt_pk_bf16(h0[0], h0[1]); w.y = cvt_pk_bf16(h0[2], h0[3]); w.z = cvt_pk_bf16(h1[0], h1[1]); w.w = cvt_pk_bf16(h1[2], h1[3]);
;                         *(gs_u32x4*)(PG8_GPTR(xg) + offb) = w;
;                         q += (o0[0] * o0[0] + o0[1] * o0[1]) + (o0[2] * o0[2] + o0[3] * o0[3]) + (o1[0] * o1[0] + o1[1] * o1[1]) + (o1[2] * o1[2] + o1[3] * o1[3]);
;                     }
;                 }
;                 if (xg) ssq_put(ssq, row, q, fr, fq);
;             }
.LBB0_1091:
	s_or_b64 exec, exec, s[2:3]
	v_ffbh_u32_e32 v0, v215
	v_min_u32_e32 v0, 32, v0
	s_waitcnt lgkmcnt(0)
	v_lshlrev_b64 v[118:119], v0, v[214:215]
	v_min_u32_e32 v118, 1, v118
	v_or_b32_e32 v118, v119, v118
	v_cvt_f32_u32_e32 v118, v118
	v_sub_u32_e32 v0, 32, v0
	v_ldexp_f32 v0, v118, v0
	v_mul_f32_e32 v0, 0x33800000, v0
	v_fmamk_f32 v0, v0, 0x3b800000, v226
	s_mov_b32 s2, 0x10000
	v_add3_u32 v137, v230, v136, s2
	v_add_u32_e32 v241, s2, v240
	v_rsq_f32_e32 v0, v0
	s_nop 0
	v_add_u32_e32 v118, 0x10000, v240
	global_load_dwordx4 v[130:133], v118, s[22:23] nt
	global_load_dwordx4 v[126:129], v118, s[22:23] offset:1024 nt
	v_add_u32_e32 v118, 0x18000, v240
	global_load_dwordx4 v[122:125], v118, s[22:23] nt
	s_nop 0
	global_load_dwordx4 v[118:121], v118, s[22:23] offset:1024 nt
	v_pk_mul_f32 v[114:115], v[114:115], v[0:1] op_sel_hi:[1,0]
	v_pk_mul_f32 v[116:117], v[116:117], v[0:1] op_sel_hi:[1,0]
	v_pk_mul_f32 v[110:111], v[110:111], v[0:1] op_sel_hi:[1,0]
	v_pk_mul_f32 v[112:113], v[112:113], v[0:1] op_sel_hi:[1,0]
	v_pk_mul_f32 v[106:107], v[106:107], v[0:1] op_sel_hi:[1,0]
	v_pk_mul_f32 v[108:109], v[108:109], v[0:1] op_sel_hi:[1,0]
	v_pk_mul_f32 v[102:103], v[102:103], v[0:1] op_sel_hi:[1,0]
	v_pk_mul_f32 v[104:105], v[104:105], v[0:1] op_sel_hi:[1,0]
	s_waitcnt vmcnt(0)
	v_lshlrev_b32_e32 v138, 16, v130
	v_and_b32_e32 v139, 0xffff0000, v130
	v_lshlrev_b32_e32 v130, 16, v131
	v_and_b32_e32 v131, 0xffff0000, v131
	v_lshlrev_b32_e32 v140, 16, v132
	v_and_b32_e32 v141, 0xffff0000, v132
	v_lshlrev_b32_e32 v132, 16, v133
	v_and_b32_e32 v133, 0xffff0000, v133
	v_pk_fma_f32 v[116:117], v[84:85], v[116:117], v[130:131]
	v_pk_fma_f32 v[114:115], v[82:83], v[114:115], v[138:139]
	v_pk_fma_f32 v[130:131], v[80:81], v[112:113], v[132:133]
	v_pk_fma_f32 v[132:133], v[78:79], v[110:111], v[140:141]
	v_cvt_pk_bf16_f32 v110, v114, v115
	v_cvt_pk_bf16_f32 v111, v116, v117
	v_pk_mul_f32 v[138:139], v[198:199], v[130:131]
	v_cvt_pk_bf16_f32 v112, v132, v133
	v_cvt_pk_bf16_f32 v113, v130, v131
	global_store_dwordx4 v241, v[110:113], s[24:25] nt
	v_pk_mul_f32 v[140:141], v[202:203], v[132:133]
	s_nop 0
	v_pk_mul_f32 v[110:111], v[204:205], v[114:115]
	v_pk_mul_f32 v[112:113], v[200:201], v[116:117]
	v_cvt_pk_bf16_f32 v110, v110, v111
	s_nop 0
	v_cvt_pk_bf16_f32 v111, v112, v113
	v_cvt_pk_bf16_f32 v112, v140, v141
	v_cvt_pk_bf16_f32 v113, v138, v139
	global_store_dwordx4 v137, v[110:113], s[26:27]
	s_nop 1
	v_mul_f32_e32 v110, v115, v115
	v_mul_f32_e32 v111, v117, v117
	v_fmac_f32_e32 v110, v114, v114
	v_fmac_f32_e32 v111, v116, v116
	v_add_f32_e32 v110, v110, v111
	v_mul_f32_e32 v111, v133, v133
	v_fmac_f32_e32 v111, v132, v132
	v_add_f32_e32 v110, v111, v110
	v_mul_f32_e32 v111, v131, v131
	v_fmac_f32_e32 v111, v130, v130
	v_add_f32_e32 v130, v111, v110
	v_lshlrev_b32_e32 v110, 16, v126
	v_and_b32_e32 v111, 0xffff0000, v126
	v_lshlrev_b32_e32 v112, 16, v127
	v_and_b32_e32 v113, 0xffff0000, v127
	v_lshlrev_b32_e32 v114, 16, v128
	v_and_b32_e32 v115, 0xffff0000, v128
	v_lshlrev_b32_e32 v116, 16, v129
	v_and_b32_e32 v117, 0xffff0000, v129
	v_pk_fma_f32 v[108:109], v[108:109], v[76:77], v[112:113]
	v_pk_fma_f32 v[106:107], v[106:107], v[74:75], v[110:111]
	v_pk_fma_f32 v[110:111], v[104:105], v[72:73], v[116:117]
	v_pk_fma_f32 v[112:113], v[102:103], v[70:71], v[114:115]
	v_cvt_pk_bf16_f32 v102, v106, v107
	v_cvt_pk_bf16_f32 v103, v108, v109
	v_pk_mul_f32 v[114:115], v[176:177], v[110:111]
	v_cvt_pk_bf16_f32 v104, v112, v113
	v_cvt_pk_bf16_f32 v105, v110, v111
	global_store_dwordx4 v241, v[102:105], s[24:25] offset:1024 nt
	v_pk_mul_f32 v[116:117], v[194:195], v[112:113]
	v_mul_f32_e32 v0, v111, v111
	v_pk_mul_f32 v[104:105], v[196:197], v[108:109]
	v_pk_mul_f32 v[102:103], v[174:175], v[106:107]
	v_fmac_f32_e32 v0, v110, v110
	v_cvt_pk_bf16_f32 v102, v102, v103
	v_cvt_pk_bf16_f32 v103, v104, v105
	v_cvt_pk_bf16_f32 v104, v116, v117
	v_cvt_pk_bf16_f32 v105, v114, v115
	global_store_dwordx4 v137, v[102:105], s[26:27] offset:256
	s_nop 1
	v_mul_f32_e32 v103, v107, v107
	v_mul_f32_e32 v104, v109, v109
	v_mul_f32_e32 v102, v113, v113
	v_fmac_f32_e32 v103, v106, v106
	v_fmac_f32_e32 v104, v108, v108
	v_fmac_f32_e32 v102, v112, v112
	v_add_f32_e32 v103, v103, v104
	v_add_f32_e32 v102, v102, v103
	v_add_f32_e32 v0, v0, v102
	v_add_f32_e32 v0, v130, v0
	ds_bpermute_b32 v102, v229, v0
	s_waitcnt lgkmcnt(0)
	v_add_f32_e32 v0, v0, v102
	ds_bpermute_b32 v102, v228, v0
	s_and_saveexec_b64 s[2:3], s[8:9]
	s_cbranch_execz .LBB0_1093
	s_waitcnt lgkmcnt(0)
	v_add_f32_e32 v0, v0, v102
	v_mul_f32_e32 v0, 0x4b800000, v0
	v_trunc_f32_e32 v0, v0
	v_mul_f32_e32 v102, 0x2f800000, v0
	v_floor_f32_e32 v103, v102
	v_fmac_f32_e32 v0, 0xcf800000, v103
	v_cvt_u32_f32_e32 v102, v0
	v_cvt_u32_f32_e32 v103, v103
	global_atomic_add_x2 v[134:135], v[102:103], off offset:256
; __device__ __forceinline__ unsigned cvt_pk_bf16(float lo, float hi) { unsigned r; asm volatile("v_cvt_pk_bf16_f32 %0, %1, %2" : "=v"(r) : "v"(lo), "v"(hi)); return r; }
; #define PG8_GPTR(p) ((__attribute__((address_space(1))) char*)(p))
;     __device__ __forceinline__ void operator()(const f32x4 (&acc)[2][2][4][2], const Unit& u, int wr, int wc, int fr, int fq) const {
;     ...
;                     bv[mm][bj] = *(gl_u32x4*)(PG8_GCPTR(base) + (unsigned)((u.pm * BM + ai * HALF + wr * 64 + (mp + mm) * 16 + fr) * DM + col0 + bj * HALF) * 2u);
; #pragma unroll
;             for (int mm = 0; mm < 2; ++mm) {
;                 const int m = mp + mm;
;                 const int row = u.pm * BM + ai * HALF + wr * 64 + m * 16 + fr; float q = 0.f;
; #pragma unroll
;                 for (int bj = 0; bj < 2; ++bj) {
;                     const unsigned offb = (unsigned)(row * DM + col0 + bj * HALF) * 2u;
;                     const u32x4 bw = bv[mm][bj];
;                     const f32x4 b0 = (f32x4){__uint_as_float(bw.x << 16), __uint_as_float(bw.x & 0xffff0000u), __uint_as_float(bw.y << 16), __uint_as_float(bw.y & 0xffff0000u)};
;                     const f32x4 b1 = (f32x4){__uint_as_float(bw.z << 16), __uint_as_float(bw.z & 0xffff0000u), __uint_as_float(bw.w << 16), __uint_as_float(bw.w & 0xffff0000u)};
;                     f32x4 a0 = acc[ai][bj][m][0], a1 = acc[ai][bj][m][1]; if constexpr (GN) { a0 *= rc[ai * 4 + m]; a1 *= rc[ai * 4 + m]; }
;                     const f32x4 o0 = b0 + g[bj][0] * a0, o1 = b1 + g[bj][1] * a1;
;                     u32x4 wo; wo.x = cvt_pk_bf16(o0[0], o0[1]); wo.y = cvt_pk_bf16(o0[2], o0[3]); wo.z = cvt_pk_bf16(o1[0], o1[1]); wo.w = cvt_pk_bf16(o1[2], o1[3]);
;                     *(gs_u32x4*)(PG8_GPTR(out) + offb) = wo;
;                     if (xg) {
;                         const f32x4 h0 = o0 * cf[bj][0], h1 = o1 * cf[bj][1];
;                         u32x4 w; w.x = cvt_pk_bf16(h0[0], h0[1]); w.y = cvt_pk_bf16(h0[2], h0[3]); w.z = cvt_pk_bf16(h1[0], h1[1]); w.w = cvt_pk_bf16(h1[2], h1[3]);
;                         *(gs_u32x4*)(PG8_GPTR(xg) + offb) = w;
;                         q += (o0[0] * o0[0] + o0[1] * o0[1]) + (o0[2] * o0[2] + o0[3] * o0[3]) + (o1[0] * o1[0] + o1[1] * o1[1]) + (o1[2] * o1[2] + o1[3] * o1[3]);
;                     }
;                 }
;                 if (xg) ssq_put(ssq, row, q, fr, fq);
;             }
.LBB0_1093:
	s_or_b64 exec, exec, s[2:3]
	v_ffbh_u32_e32 v0, v213
	v_min_u32_e32 v0, 32, v0
	s_waitcnt lgkmcnt(0)
	v_lshlrev_b64 v[102:103], v0, v[212:213]
	v_min_u32_e32 v102, 1, v102
	v_or_b32_e32 v102, v103, v102
	v_cvt_f32_u32_e32 v102, v102
	v_sub_u32_e32 v0, 32, v0
	v_and_b32_e32 v107, 0xffff0000, v124
	v_lshlrev_b32_e32 v108, 16, v125
	v_ldexp_f32 v0, v102, v0
	v_mul_f32_e32 v0, 0x33800000, v0
	v_fmamk_f32 v0, v0, 0x3b800000, v226
	v_and_b32_e32 v109, 0xffff0000, v125
	s_nop 0
	s_mov_b32 s2, 0x18000
	v_add3_u32 v110, v230, v136, s2
	v_add_u32_e32 v241, s2, v240
	v_rsq_f32_e32 v0, v0
	s_nop 0
	v_lshlrev_b32_e32 v102, 16, v122
	v_and_b32_e32 v103, 0xffff0000, v122
	v_lshlrev_b32_e32 v104, 16, v123
	v_and_b32_e32 v105, 0xffff0000, v123
	v_lshlrev_b32_e32 v106, 16, v124
	v_pk_mul_f32 v[98:99], v[98:99], v[0:1] op_sel_hi:[1,0]
	v_pk_mul_f32 v[100:101], v[100:101], v[0:1] op_sel_hi:[1,0]
	v_pk_mul_f32 v[94:95], v[94:95], v[0:1] op_sel_hi:[1,0]
	v_pk_mul_f32 v[96:97], v[96:97], v[0:1] op_sel_hi:[1,0]
	v_pk_fma_f32 v[100:101], v[84:85], v[100:101], v[104:105]
	v_pk_fma_f32 v[98:99], v[82:83], v[98:99], v[102:103]
	v_pk_fma_f32 v[104:105], v[78:79], v[94:95], v[106:107]
	v_cvt_pk_bf16_f32 v94, v98, v99
	v_cvt_pk_bf16_f32 v95, v100, v101
	v_pk_fma_f32 v[102:103], v[80:81], v[96:97], v[108:109]
	v_cvt_pk_bf16_f32 v96, v104, v105
	v_pk_mul_f32 v[108:109], v[202:203], v[104:105]
	v_cvt_pk_bf16_f32 v97, v102, v103
	global_store_dwordx4 v241, v[94:97], s[24:25] nt
	v_pk_mul_f32 v[106:107], v[198:199], v[102:103]
	v_pk_mul_f32 v[90:91], v[90:91], v[0:1] op_sel_hi:[1,0]
	v_pk_mul_f32 v[94:95], v[204:205], v[98:99]
	v_pk_mul_f32 v[96:97], v[200:201], v[100:101]
	v_cvt_pk_bf16_f32 v94, v94, v95
	v_pk_mul_f32 v[92:93], v[92:93], v[0:1] op_sel_hi:[1,0]
	v_cvt_pk_bf16_f32 v95, v96, v97
	v_cvt_pk_bf16_f32 v96, v108, v109
	v_cvt_pk_bf16_f32 v97, v106, v107
	global_store_dwordx4 v110, v[94:97], s[26:27]
	v_pk_mul_f32 v[86:87], v[86:87], v[0:1] op_sel_hi:[1,0]
	v_pk_mul_f32 v[88:89], v[88:89], v[0:1] op_sel_hi:[1,0]
	v_mul_f32_e32 v94, v99, v99
	v_mul_f32_e32 v95, v101, v101
	v_fmac_f32_e32 v94, v98, v98
	v_fmac_f32_e32 v95, v100, v100
	v_add_f32_e32 v94, v94, v95
	v_mul_f32_e32 v95, v105, v105
	v_fmac_f32_e32 v95, v104, v104
	v_add_f32_e32 v94, v95, v94
	v_mul_f32_e32 v95, v103, v103
	v_fmac_f32_e32 v95, v102, v102
	v_add_f32_e32 v102, v95, v94
	v_lshlrev_b32_e32 v94, 16, v118
	v_and_b32_e32 v95, 0xffff0000, v118
	v_lshlrev_b32_e32 v96, 16, v119
	v_and_b32_e32 v97, 0xffff0000, v119
	v_lshlrev_b32_e32 v98, 16, v120
	v_and_b32_e32 v99, 0xffff0000, v120
	v_lshlrev_b32_e32 v100, 16, v121
	v_and_b32_e32 v101, 0xffff0000, v121
	v_pk_fma_f32 v[92:93], v[92:93], v[76:77], v[96:97]
	v_pk_fma_f32 v[90:91], v[90:91], v[74:75], v[94:95]
	v_pk_fma_f32 v[94:95], v[88:89], v[72:73], v[100:101]
	v_pk_fma_f32 v[96:97], v[86:87], v[70:71], v[98:99]
	v_cvt_pk_bf16_f32 v86, v90, v91
	v_cvt_pk_bf16_f32 v87, v92, v93
	v_mul_f32_e32 v0, v95, v95
	v_cvt_pk_bf16_f32 v88, v96, v97
	v_cvt_pk_bf16_f32 v89, v94, v95
	global_store_dwordx4 v241, v[86:89], s[24:25] offset:1024 nt
	v_fmac_f32_e32 v0, v94, v94
	v_pk_mul_f32 v[98:99], v[196:197], v[92:93]
	v_mul_f32_e32 v87, v91, v91
	v_mul_f32_e32 v88, v93, v93
	v_mul_f32_e32 v86, v97, v97
	v_fmac_f32_e32 v87, v90, v90
	v_fmac_f32_e32 v88, v92, v92
	v_fmac_f32_e32 v86, v96, v96
	v_add_f32_e32 v87, v87, v88
	v_add_f32_e32 v86, v86, v87
	v_add_f32_e32 v0, v0, v86
	v_add_f32_e32 v0, v102, v0
	ds_bpermute_b32 v89, v229, v0
	v_pk_mul_f32 v[86:87], v[174:175], v[90:91]
	v_pk_mul_f32 v[90:91], v[194:195], v[96:97]
	v_cvt_pk_bf16_f32 v88, v86, v87
	v_pk_mul_f32 v[92:93], v[176:177], v[94:95]
	s_waitcnt lgkmcnt(0)
	v_add_f32_e32 v0, v0, v89
	ds_bpermute_b32 v86, v228, v0
	v_cvt_pk_bf16_f32 v89, v98, v99
	v_cvt_pk_bf16_f32 v90, v90, v91
	v_cvt_pk_bf16_f32 v91, v92, v93
	global_store_dwordx4 v110, v[88:91], s[26:27] offset:256
	s_and_saveexec_b64 s[2:3], s[8:9]
	s_cbranch_execz .LBB0_1095
	s_waitcnt lgkmcnt(0)
	v_add_f32_e32 v0, v0, v86
	v_mul_f32_e32 v0, 0x4b800000, v0
	v_trunc_f32_e32 v0, v0
	v_mul_f32_e32 v86, 0x2f800000, v0
	v_floor_f32_e32 v87, v86
	v_fmac_f32_e32 v0, 0xcf800000, v87
	v_cvt_u32_f32_e32 v86, v0
	v_cvt_u32_f32_e32 v87, v87
	global_atomic_add_x2 v[134:135], v[86:87], off offset:384
; __device__ __forceinline__ unsigned cvt_pk_bf16(float lo, float hi) { unsigned r; asm volatile("v_cvt_pk_bf16_f32 %0, %1, %2" : "=v"(r) : "v"(lo), "v"(hi)); return r; }
; #define PG8_GPTR(p) ((__attribute__((address_space(1))) char*)(p))
;     __device__ __forceinline__ void operator()(const f32x4 (&acc)[2][2][4][2], const Unit& u, int wr, int wc, int fr, int fq) const {
;     ...
;                     bv[mm][bj] = *(gl_u32x4*)(PG8_GCPTR(base) + (unsigned)((u.pm * BM + ai * HALF + wr * 64 + (mp + mm) * 16 + fr) * DM + col0 + bj * HALF) * 2u);
; #pragma unroll
;             for (int mm = 0; mm < 2; ++mm) {
;                 const int m = mp + mm;
;                 const int row = u.pm * BM + ai * HALF + wr * 64 + m * 16 + fr; float q = 0.f;
; #pragma unroll
;                 for (int bj = 0; bj < 2; ++bj) {
;                     const unsigned offb = (unsigned)(row * DM + col0 + bj * HALF) * 2u;
;                     const u32x4 bw = bv[mm][bj];
;                     const f32x4 b0 = (f32x4){__uint_as_float(bw.x << 16), __uint_as_float(bw.x & 0xffff0000u), __uint_as_float(bw.y << 16), __uint_as_float(bw.y & 0xffff0000u)};
;                     const f32x4 b1 = (f32x4){__uint_as_float(bw.z << 16), __uint_as_float(bw.z & 0xffff0000u), __uint_as_float(bw.w << 16), __uint_as_float(bw.w & 0xffff0000u)};
;                     f32x4 a0 = acc[ai][bj][m][0], a1 = acc[ai][bj][m][1]; if constexpr (GN) { a0 *= rc[ai * 4 + m]; a1 *= rc[ai * 4 + m]; }
;                     const f32x4 o0 = b0 + g[bj][0] * a0, o1 = b1 + g[bj][1] * a1;
;                     u32x4 wo; wo.x = cvt_pk_bf16(o0[0], o0[1]); wo.y = cvt_pk_bf16(o0[2], o0[3]); wo.z = cvt_pk_bf16(o1[0], o1[1]); wo.w = cvt_pk_bf16(o1[2], o1[3]);
;                     *(gs_u32x4*)(PG8_GPTR(out) + offb) = wo;
;                     if (xg) {
;                         const f32x4 h0 = o0 * cf[bj][0], h1 = o1 * cf[bj][1];
;                         u32x4 w; w.x = cvt_pk_bf16(h0[0], h0[1]); w.y = cvt_pk_bf16(h0[2], h0[3]); w.z = cvt_pk_bf16(h1[0], h1[1]); w.w = cvt_pk_bf16(h1[2], h1[3]);
;                         *(gs_u32x4*)(PG8_GPTR(xg) + offb) = w;
;                         q += (o0[0] * o0[0] + o0[1] * o0[1]) + (o0[2] * o0[2] + o0[3] * o0[3]) + (o1[0] * o1[0] + o1[1] * o1[1]) + (o1[2] * o1[2] + o1[3] * o1[3]);
;                     }
;                 }
;                 if (xg) ssq_put(ssq, row, q, fr, fq);
;             }
.LBB0_1095:
	s_or_b64 exec, exec, s[2:3]
	v_ffbh_u32_e32 v0, v211
	v_min_u32_e32 v0, 32, v0
	s_waitcnt lgkmcnt(0)
	v_lshlrev_b64 v[86:87], v0, v[210:211]
	v_min_u32_e32 v86, 1, v86
	v_or_b32_e32 v86, v87, v86
	v_cvt_f32_u32_e32 v86, v86
	v_sub_u32_e32 v0, 32, v0
	v_ldexp_f32 v0, v86, v0
	v_mul_f32_e32 v0, 0x33800000, v0
	v_fmamk_f32 v0, v0, 0x3b800000, v226
	s_mov_b32 s2, 0x40000
	v_add3_u32 v106, v232, v230, s2
	v_add_u32_e32 v241, s2, v240
	v_rsq_f32_e32 v0, v0
	s_nop 0
	v_add_u32_e32 v86, 0x40000, v240
	global_load_dwordx4 v[98:101], v86, s[22:23] nt
	global_load_dwordx4 v[94:97], v86, s[22:23] offset:1024 nt
	v_add_u32_e32 v86, 0x48000, v240
	global_load_dwordx4 v[90:93], v86, s[22:23] nt
	s_nop 0
	global_load_dwordx4 v[86:89], v86, s[22:23] offset:1024 nt
	v_pk_mul_f32 v[66:67], v[66:67], v[0:1] op_sel_hi:[1,0]
	v_pk_mul_f32 v[68:69], v[68:69], v[0:1] op_sel_hi:[1,0]
	v_pk_mul_f32 v[62:63], v[62:63], v[0:1] op_sel_hi:[1,0]
	v_pk_mul_f32 v[64:65], v[64:65], v[0:1] op_sel_hi:[1,0]
	v_pk_mul_f32 v[58:59], v[58:59], v[0:1] op_sel_hi:[1,0]
	v_pk_mul_f32 v[60:61], v[60:61], v[0:1] op_sel_hi:[1,0]
	v_pk_mul_f32 v[54:55], v[54:55], v[0:1] op_sel_hi:[1,0]
	v_pk_mul_f32 v[56:57], v[56:57], v[0:1] op_sel_hi:[1,0]
	s_waitcnt vmcnt(0)
	v_lshlrev_b32_e32 v102, 16, v98
	v_and_b32_e32 v103, 0xffff0000, v98
	v_lshlrev_b32_e32 v98, 16, v99
	v_and_b32_e32 v99, 0xffff0000, v99
	v_lshlrev_b32_e32 v104, 16, v100
	v_and_b32_e32 v105, 0xffff0000, v100
	v_lshlrev_b32_e32 v100, 16, v101
	v_and_b32_e32 v101, 0xffff0000, v101
	v_pk_fma_f32 v[68:69], v[84:85], v[68:69], v[98:99]
	v_pk_fma_f32 v[66:67], v[82:83], v[66:67], v[102:103]
	v_pk_fma_f32 v[98:99], v[80:81], v[64:65], v[100:101]
	v_pk_fma_f32 v[100:101], v[78:79], v[62:63], v[104:105]
	v_cvt_pk_bf16_f32 v62, v66, v67
	v_cvt_pk_bf16_f32 v63, v68, v69
	v_pk_mul_f32 v[102:103], v[198:199], v[98:99]
	v_cvt_pk_bf16_f32 v64, v100, v101
	v_cvt_pk_bf16_f32 v65, v98, v99
	global_store_dwordx4 v241, v[62:65], s[24:25] nt
	v_pk_mul_f32 v[104:105], v[202:203], v[100:101]
	s_nop 0
	v_pk_mul_f32 v[62:63], v[204:205], v[66:67]
	v_pk_mul_f32 v[64:65], v[200:201], v[68:69]
	v_cvt_pk_bf16_f32 v62, v62, v63
	s_nop 0
	v_cvt_pk_bf16_f32 v63, v64, v65
	v_cvt_pk_bf16_f32 v64, v104, v105
	v_cvt_pk_bf16_f32 v65, v102, v103
	global_store_dwordx4 v106, v[62:65], s[26:27]
	s_nop 1
	v_mul_f32_e32 v62, v67, v67
	v_mul_f32_e32 v63, v69, v69
	v_fmac_f32_e32 v62, v66, v66
	v_fmac_f32_e32 v63, v68, v68
	v_add_f32_e32 v62, v62, v63
	v_mul_f32_e32 v63, v101, v101
	v_fmac_f32_e32 v63, v100, v100
	v_add_f32_e32 v62, v63, v62
	v_mul_f32_e32 v63, v99, v99
	v_fmac_f32_e32 v63, v98, v98
	v_add_f32_e32 v98, v63, v62
	v_lshlrev_b32_e32 v62, 16, v94
	v_and_b32_e32 v63, 0xffff0000, v94
	v_lshlrev_b32_e32 v64, 16, v95
	v_and_b32_e32 v65, 0xffff0000, v95
	v_lshlrev_b32_e32 v66, 16, v96
	v_and_b32_e32 v67, 0xffff0000, v96
	v_lshlrev_b32_e32 v68, 16, v97
	v_and_b32_e32 v69, 0xffff0000, v97
	v_pk_fma_f32 v[60:61], v[60:61], v[76:77], v[64:65]
	v_pk_fma_f32 v[58:59], v[58:59], v[74:75], v[62:63]
	v_pk_fma_f32 v[62:63], v[56:57], v[72:73], v[68:69]
	v_pk_fma_f32 v[64:65], v[54:55], v[70:71], v[66:67]
	v_cvt_pk_bf16_f32 v54, v58, v59
	v_cvt_pk_bf16_f32 v55, v60, v61
	v_pk_mul_f32 v[66:67], v[176:177], v[62:63]
	v_cvt_pk_bf16_f32 v56, v64, v65
	v_cvt_pk_bf16_f32 v57, v62, v63
	global_store_dwordx4 v241, v[54:57], s[24:25] offset:1024 nt
	v_pk_mul_f32 v[68:69], v[194:195], v[64:65]
	v_mul_f32_e32 v0, v63, v63
	v_pk_mul_f32 v[56:57], v[196:197], v[60:61]
	v_pk_mul_f32 v[54:55], v[174:175], v[58:59]
	v_fmac_f32_e32 v0, v62, v62
	v_cvt_pk_bf16_f32 v54, v54, v55
	v_cvt_pk_bf16_f32 v55, v56, v57
	v_cvt_pk_bf16_f32 v56, v68, v69
	v_cvt_pk_bf16_f32 v57, v66, v67
	global_store_dwordx4 v106, v[54:57], s[26:27] offset:256
	s_nop 1
	v_mul_f32_e32 v55, v59, v59
	v_mul_f32_e32 v56, v61, v61
	v_mul_f32_e32 v54, v65, v65
	v_fmac_f32_e32 v55, v58, v58
	v_fmac_f32_e32 v56, v60, v60
	v_fmac_f32_e32 v54, v64, v64
	v_add_f32_e32 v55, v55, v56
	v_add_f32_e32 v54, v54, v55
	v_add_f32_e32 v0, v0, v54
	v_add_f32_e32 v0, v98, v0
	ds_bpermute_b32 v54, v229, v0
	s_waitcnt lgkmcnt(0)
	v_add_f32_e32 v0, v0, v54
	ds_bpermute_b32 v54, v228, v0
	s_and_saveexec_b64 s[2:3], s[8:9]
	s_cbranch_execz .LBB0_1097
	s_waitcnt lgkmcnt(0)
	v_add_f32_e32 v0, v0, v54
	v_mul_f32_e32 v0, 0x4b800000, v0
	v_trunc_f32_e32 v0, v0
	v_mul_f32_e32 v54, 0x2f800000, v0
	v_floor_f32_e32 v55, v54
	v_fmac_f32_e32 v0, 0xcf800000, v55
	v_cvt_u32_f32_e32 v54, v0
	v_cvt_u32_f32_e32 v55, v55
	global_atomic_add_x2 v[134:135], v[54:55], off offset:1024
; __device__ __forceinline__ unsigned cvt_pk_bf16(float lo, float hi) { unsigned r; asm volatile("v_cvt_pk_bf16_f32 %0, %1, %2" : "=v"(r) : "v"(lo), "v"(hi)); return r; }
; #define PG8_GPTR(p) ((__attribute__((address_space(1))) char*)(p))
;     __device__ __forceinline__ void operator()(const f32x4 (&acc)[2][2][4][2], const Unit& u, int wr, int wc, int fr, int fq) const {
;     ...
;                     bv[mm][bj] = *(gl_u32x4*)(PG8_GCPTR(base) + (unsigned)((u.pm * BM + ai * HALF + wr * 64 + (mp + mm) * 16 + fr) * DM + col0 + bj * HALF) * 2u);
; #pragma unroll
;             for (int mm = 0; mm < 2; ++mm) {
;                 const int m = mp + mm;
;                 const int row = u.pm * BM + ai * HALF + wr * 64 + m * 16 + fr; float q = 0.f;
; #pragma unroll
;                 for (int bj = 0; bj < 2; ++bj) {
;                     const unsigned offb = (unsigned)(row * DM + col0 + bj * HALF) * 2u;
;                     const u32x4 bw = bv[mm][bj];
;                     const f32x4 b0 = (f32x4){__uint_as_float(bw.x << 16), __uint_as_float(bw.x & 0xffff0000u), __uint_as_float(bw.y << 16), __uint_as_float(bw.y & 0xffff0000u)};
;                     const f32x4 b1 = (f32x4){__uint_as_float(bw.z << 16), __uint_as_float(bw.z & 0xffff0000u), __uint_as_float(bw.w << 16), __uint_as_float(bw.w & 0xffff0000u)};
;                     f32x4 a0 = acc[ai][bj][m][0], a1 = acc[ai][bj][m][1]; if constexpr (GN) { a0 *= rc[ai * 4 + m]; a1 *= rc[ai * 4 + m]; }
;                     const f32x4 o0 = b0 + g[bj][0] * a0, o1 = b1 + g[bj][1] * a1;
;                     u32x4 wo; wo.x = cvt_pk_bf16(o0[0], o0[1]); wo.y = cvt_pk_bf16(o0[2], o0[3]); wo.z = cvt_pk_bf16(o1[0], o1[1]); wo.w = cvt_pk_bf16(o1[2], o1[3]);
;                     *(gs_u32x4*)(PG8_GPTR(out) + offb) = wo;
;                     if (xg) {
;                         const f32x4 h0 = o0 * cf[bj][0], h1 = o1 * cf[bj][1];
;                         u32x4 w; w.x = cvt_pk_bf16(h0[0], h0[1]); w.y = cvt_pk_bf16(h0[2], h0[3]); w.z = cvt_pk_bf16(h1[0], h1[1]); w.w = cvt_pk_bf16(h1[2], h1[3]);
;                         *(gs_u32x4*)(PG8_GPTR(xg) + offb) = w;
;                         q += (o0[0] * o0[0] + o0[1] * o0[1]) + (o0[2] * o0[2] + o0[3] * o0[3]) + (o1[0] * o1[0] + o1[1] * o1[1]) + (o1[2] * o1[2] + o1[3] * o1[3]);
;                     }
;                 }
;                 if (xg) ssq_put(ssq, row, q, fr, fq);
;             }
.LBB0_1097:
	s_or_b64 exec, exec, s[2:3]
	v_ffbh_u32_e32 v0, v209
	v_min_u32_e32 v0, 32, v0
	s_waitcnt lgkmcnt(0)
	v_lshlrev_b64 v[54:55], v0, v[208:209]
	v_min_u32_e32 v54, 1, v54
	v_or_b32_e32 v54, v55, v54
	v_cvt_f32_u32_e32 v54, v54
	v_sub_u32_e32 v0, 32, v0
	v_and_b32_e32 v59, 0xffff0000, v92
	v_lshlrev_b32_e32 v60, 16, v93
	v_ldexp_f32 v0, v54, v0
	v_mul_f32_e32 v0, 0x33800000, v0
	v_fmamk_f32 v0, v0, 0x3b800000, v226
	v_and_b32_e32 v61, 0xffff0000, v93
	s_nop 0
	s_mov_b32 s2, 0x48000
	v_add3_u32 v62, v136, v230, s2
	v_add_u32_e32 v241, s2, v240
	v_rsq_f32_e32 v0, v0
	s_nop 0
	v_lshlrev_b32_e32 v54, 16, v90
	v_and_b32_e32 v55, 0xffff0000, v90
	v_lshlrev_b32_e32 v56, 16, v91
	v_and_b32_e32 v57, 0xffff0000, v91
	v_lshlrev_b32_e32 v58, 16, v92
	v_pk_mul_f32 v[50:51], v[50:51], v[0:1] op_sel_hi:[1,0]
	v_pk_mul_f32 v[52:53], v[52:53], v[0:1] op_sel_hi:[1,0]
	v_pk_mul_f32 v[46:47], v[46:47], v[0:1] op_sel_hi:[1,0]
	v_pk_mul_f32 v[48:49], v[48:49], v[0:1] op_sel_hi:[1,0]
	v_pk_fma_f32 v[52:53], v[84:85], v[52:53], v[56:57]
	v_pk_fma_f32 v[50:51], v[82:83], v[50:51], v[54:55]
	v_pk_fma_f32 v[56:57], v[78:79], v[46:47], v[58:59]
	v_cvt_pk_bf16_f32 v46, v50, v51
	v_cvt_pk_bf16_f32 v47, v52, v53
	v_pk_fma_f32 v[54:55], v[80:81], v[48:49], v[60:61]
	v_cvt_pk_bf16_f32 v48, v56, v57
	v_pk_mul_f32 v[60:61], v[202:203], v[56:57]
	v_cvt_pk_bf16_f32 v49, v54, v55
	global_store_dwordx4 v241, v[46:49], s[24:25] nt
	v_pk_mul_f32 v[58:59], v[198:199], v[54:55]
	v_pk_mul_f32 v[42:43], v[42:43], v[0:1] op_sel_hi:[1,0]
	v_pk_mul_f32 v[46:47], v[204:205], v[50:51]
	v_pk_mul_f32 v[48:49], v[200:201], v[52:53]
	v_cvt_pk_bf16_f32 v46, v46, v47
	v_pk_mul_f32 v[44:45], v[44:45], v[0:1] op_sel_hi:[1,0]
	v_cvt_pk_bf16_f32 v47, v48, v49
	v_cvt_pk_bf16_f32 v48, v60, v61
	v_cvt_pk_bf16_f32 v49, v58, v59
	global_store_dwordx4 v62, v[46:49], s[26:27]
	v_pk_mul_f32 v[38:39], v[38:39], v[0:1] op_sel_hi:[1,0]
	v_pk_mul_f32 v[40:41], v[40:41], v[0:1] op_sel_hi:[1,0]
	v_mul_f32_e32 v46, v51, v51
	v_mul_f32_e32 v47, v53, v53
	v_fmac_f32_e32 v46, v50, v50
	v_fmac_f32_e32 v47, v52, v52
	v_add_f32_e32 v46, v46, v47
	v_mul_f32_e32 v47, v57, v57
	v_fmac_f32_e32 v47, v56, v56
	v_add_f32_e32 v46, v47, v46
	v_mul_f32_e32 v47, v55, v55
	v_fmac_f32_e32 v47, v54, v54
	v_add_f32_e32 v54, v47, v46
	v_lshlrev_b32_e32 v46, 16, v86
	v_and_b32_e32 v47, 0xffff0000, v86
	v_lshlrev_b32_e32 v48, 16, v87
	v_and_b32_e32 v49, 0xffff0000, v87
	v_lshlrev_b32_e32 v50, 16, v88
	v_and_b32_e32 v51, 0xffff0000, v88
	v_lshlrev_b32_e32 v52, 16, v89
	v_and_b32_e32 v53, 0xffff0000, v89
	v_pk_fma_f32 v[44:45], v[76:77], v[44:45], v[48:49]
	v_pk_fma_f32 v[42:43], v[74:75], v[42:43], v[46:47]
	v_pk_fma_f32 v[46:47], v[40:41], v[72:73], v[52:53]
	v_pk_fma_f32 v[48:49], v[38:39], v[70:71], v[50:51]
	v_cvt_pk_bf16_f32 v38, v42, v43
	v_cvt_pk_bf16_f32 v39, v44, v45
	v_mul_f32_e32 v0, v47, v47
	v_cvt_pk_bf16_f32 v40, v48, v49
	v_cvt_pk_bf16_f32 v41, v46, v47
	global_store_dwordx4 v241, v[38:41], s[24:25] offset:1024 nt
	v_fmac_f32_e32 v0, v46, v46
	v_pk_mul_f32 v[50:51], v[196:197], v[44:45]
	v_mul_f32_e32 v39, v43, v43
	v_mul_f32_e32 v40, v45, v45
	v_mul_f32_e32 v38, v49, v49
	v_fmac_f32_e32 v39, v42, v42
	v_fmac_f32_e32 v40, v44, v44
	v_fmac_f32_e32 v38, v48, v48
	v_add_f32_e32 v39, v39, v40
	v_add_f32_e32 v38, v38, v39
	v_add_f32_e32 v0, v0, v38
	v_add_f32_e32 v0, v54, v0
	ds_bpermute_b32 v41, v229, v0
	v_pk_mul_f32 v[38:39], v[174:175], v[42:43]
	v_pk_mul_f32 v[42:43], v[194:195], v[48:49]
	v_cvt_pk_bf16_f32 v40, v38, v39
	v_pk_mul_f32 v[44:45], v[176:177], v[46:47]
	s_waitcnt lgkmcnt(0)
	v_add_f32_e32 v0, v0, v41
	ds_bpermute_b32 v38, v228, v0
	v_cvt_pk_bf16_f32 v41, v50, v51
	v_cvt_pk_bf16_f32 v42, v42, v43
	v_cvt_pk_bf16_f32 v43, v44, v45
	global_store_dwordx4 v62, v[40:43], s[26:27] offset:256
	s_and_saveexec_b64 s[2:3], s[8:9]
	s_cbranch_execz .LBB0_1099
	s_waitcnt lgkmcnt(0)
	v_add_f32_e32 v0, v0, v38
	v_mul_f32_e32 v0, 0x4b800000, v0
	v_trunc_f32_e32 v0, v0
	v_mul_f32_e32 v38, 0x2f800000, v0
	v_floor_f32_e32 v39, v38
	v_fmac_f32_e32 v0, 0xcf800000, v39
	v_cvt_u32_f32_e32 v38, v0
	v_cvt_u32_f32_e32 v39, v39
	global_atomic_add_x2 v[134:135], v[38:39], off offset:1152
.LBB0_1099:
	s_or_b64 exec, exec, s[2:3]
	v_ffbh_u32_e32 v0, v207
	v_min_u32_e32 v0, 32, v0
	s_waitcnt lgkmcnt(0)
	v_lshlrev_b64 v[38:39], v0, v[206:207]
	v_min_u32_e32 v38, 1, v38
	v_or_b32_e32 v38, v39, v38
	v_cvt_f32_u32_e32 v38, v38
	v_sub_u32_e32 v0, 32, v0
	v_ldexp_f32 v0, v38, v0
	v_mul_f32_e32 v0, 0x33800000, v0
	v_fmamk_f32 v0, v0, 0x3b800000, v226
	s_mov_b32 s2, 0x50000
	v_add3_u32 v58, v136, v230, s2
	v_add_u32_e32 v241, s2, v240
	v_rsq_f32_e32 v0, v0
	s_nop 0
	v_add_u32_e32 v38, 0x50000, v240
	global_load_dwordx4 v[50:53], v38, s[22:23] nt
	global_load_dwordx4 v[46:49], v38, s[22:23] offset:1024 nt
	v_add_u32_e32 v38, 0x58000, v240
	global_load_dwordx4 v[42:45], v38, s[22:23] nt
	s_nop 0
	global_load_dwordx4 v[38:41], v38, s[22:23] offset:1024 nt
	v_pk_mul_f32 v[34:35], v[34:35], v[0:1] op_sel_hi:[1,0]
	v_pk_mul_f32 v[36:37], v[36:37], v[0:1] op_sel_hi:[1,0]
	v_pk_mul_f32 v[30:31], v[30:31], v[0:1] op_sel_hi:[1,0]
	v_pk_mul_f32 v[32:33], v[32:33], v[0:1] op_sel_hi:[1,0]
	v_pk_mul_f32 v[26:27], v[26:27], v[0:1] op_sel_hi:[1,0]
	v_pk_mul_f32 v[28:29], v[28:29], v[0:1] op_sel_hi:[1,0]
	v_pk_mul_f32 v[22:23], v[22:23], v[0:1] op_sel_hi:[1,0]
	v_pk_mul_f32 v[24:25], v[24:25], v[0:1] op_sel_hi:[1,0]
	s_waitcnt vmcnt(0)
; __device__ __forceinline__ unsigned cvt_pk_bf16(float lo, float hi) { unsigned r; asm volatile("v_cvt_pk_bf16_f32 %0, %1, %2" : "=v"(r) : "v"(lo), "v"(hi)); return r; }
; #define PG8_GPTR(p) ((__attribute__((address_space(1))) char*)(p))
;     __device__ __forceinline__ void operator()(const f32x4 (&acc)[2][2][4][2], const Unit& u, int wr, int wc, int fr, int fq) const {
;     ...
;                     bv[mm][bj] = *(gl_u32x4*)(PG8_GCPTR(base) + (unsigned)((u.pm * BM + ai * HALF + wr * 64 + (mp + mm) * 16 + fr) * DM + col0 + bj * HALF) * 2u);
; #pragma unroll
;             for (int mm = 0; mm < 2; ++mm) {
;                 const int m = mp + mm;
;                 const int row = u.pm * BM + ai * HALF + wr * 64 + m * 16 + fr; float q = 0.f;
; #pragma unroll
;                 for (int bj = 0; bj < 2; ++bj) {
;                     const unsigned offb = (unsigned)(row * DM + col0 + bj * HALF) * 2u;
;                     const u32x4 bw = bv[mm][bj];
;                     const f32x4 b0 = (f32x4){__uint_as_float(bw.x << 16), __uint_as_float(bw.x & 0xffff0000u), __uint_as_float(bw.y << 16), __uint_as_float(bw.y & 0xffff0000u)};
;                     const f32x4 b1 = (f32x4){__uint_as_float(bw.z << 16), __uint_as_float(bw.z & 0xffff0000u), __uint_as_float(bw.w << 16), __uint_as_float(bw.w & 0xffff0000u)};
;                     f32x4 a0 = acc[ai][bj][m][0], a1 = acc[ai][bj][m][1]; if constexpr (GN) { a0 *= rc[ai * 4 + m]; a1 *= rc[ai * 4 + m]; }
;                     const f32x4 o0 = b0 + g[bj][0] * a0, o1 = b1 + g[bj][1] * a1;
;                     u32x4 wo; wo.x = cvt_pk_bf16(o0[0], o0[1]); wo.y = cvt_pk_bf16(o0[2], o0[3]); wo.z = cvt_pk_bf16(o1[0], o1[1]); wo.w = cvt_pk_bf16(o1[2], o1[3]);
;                     *(gs_u32x4*)(PG8_GPTR(out) + offb) = wo;
;                     if (xg) {
;                         const f32x4 h0 = o0 * cf[bj][0], h1 = o1 * cf[bj][1];
;                         u32x4 w; w.x = cvt_pk_bf16(h0[0], h0[1]); w.y = cvt_pk_bf16(h0[2], h0[3]); w.z = cvt_pk_bf16(h1[0], h1[1]); w.w = cvt_pk_bf16(h1[2], h1[3]);
;                         *(gs_u32x4*)(PG8_GPTR(xg) + offb) = w;
;                         q += (o0[0] * o0[0] + o0[1] * o0[1]) + (o0[2] * o0[2] + o0[3] * o0[3]) + (o1[0] * o1[0] + o1[1] * o1[1]) + (o1[2] * o1[2] + o1[3] * o1[3]);
;                     }
;                 }
;                 if (xg) ssq_put(ssq, row, q, fr, fq);
;             }
	v_lshlrev_b32_e32 v54, 16, v50
	v_and_b32_e32 v55, 0xffff0000, v50
	v_lshlrev_b32_e32 v50, 16, v51
	v_and_b32_e32 v51, 0xffff0000, v51
	v_lshlrev_b32_e32 v56, 16, v52
	v_and_b32_e32 v57, 0xffff0000, v52
	v_lshlrev_b32_e32 v52, 16, v53
	v_and_b32_e32 v53, 0xffff0000, v53
	v_pk_fma_f32 v[36:37], v[84:85], v[36:37], v[50:51]
	v_pk_fma_f32 v[34:35], v[82:83], v[34:35], v[54:55]
	v_pk_fma_f32 v[50:51], v[80:81], v[32:33], v[52:53]
	v_pk_fma_f32 v[52:53], v[78:79], v[30:31], v[56:57]
	v_cvt_pk_bf16_f32 v30, v34, v35
	v_cvt_pk_bf16_f32 v31, v36, v37
	v_pk_mul_f32 v[54:55], v[198:199], v[50:51]
	v_cvt_pk_bf16_f32 v32, v52, v53
	v_cvt_pk_bf16_f32 v33, v50, v51
	global_store_dwordx4 v241, v[30:33], s[24:25] nt
	v_pk_mul_f32 v[56:57], v[202:203], v[52:53]
	s_nop 0
	v_pk_mul_f32 v[30:31], v[204:205], v[34:35]
	v_pk_mul_f32 v[32:33], v[200:201], v[36:37]
	v_cvt_pk_bf16_f32 v30, v30, v31
	s_nop 0
	v_cvt_pk_bf16_f32 v31, v32, v33
	v_cvt_pk_bf16_f32 v32, v56, v57
	v_cvt_pk_bf16_f32 v33, v54, v55
	global_store_dwordx4 v58, v[30:33], s[26:27]
	s_nop 1
	v_mul_f32_e32 v30, v35, v35
	v_mul_f32_e32 v31, v37, v37
	v_fmac_f32_e32 v30, v34, v34
	v_fmac_f32_e32 v31, v36, v36
	v_add_f32_e32 v30, v30, v31
	v_mul_f32_e32 v31, v53, v53
	v_fmac_f32_e32 v31, v52, v52
	v_add_f32_e32 v30, v31, v30
	v_mul_f32_e32 v31, v51, v51
	v_fmac_f32_e32 v31, v50, v50
	v_add_f32_e32 v50, v31, v30
	v_lshlrev_b32_e32 v30, 16, v46
	v_and_b32_e32 v31, 0xffff0000, v46
	v_lshlrev_b32_e32 v32, 16, v47
	v_and_b32_e32 v33, 0xffff0000, v47
	v_lshlrev_b32_e32 v34, 16, v48
	v_and_b32_e32 v35, 0xffff0000, v48
	v_lshlrev_b32_e32 v36, 16, v49
	v_and_b32_e32 v37, 0xffff0000, v49
	v_pk_fma_f32 v[28:29], v[76:77], v[28:29], v[32:33]
	v_pk_fma_f32 v[26:27], v[74:75], v[26:27], v[30:31]
	v_pk_fma_f32 v[30:31], v[72:73], v[24:25], v[36:37]
	v_pk_fma_f32 v[32:33], v[70:71], v[22:23], v[34:35]
	v_cvt_pk_bf16_f32 v22, v26, v27
	v_cvt_pk_bf16_f32 v23, v28, v29
	v_pk_mul_f32 v[34:35], v[176:177], v[30:31]
	v_cvt_pk_bf16_f32 v24, v32, v33
	v_cvt_pk_bf16_f32 v25, v30, v31
	global_store_dwordx4 v241, v[22:25], s[24:25] offset:1024 nt
	v_pk_mul_f32 v[36:37], v[194:195], v[32:33]
	v_mul_f32_e32 v0, v31, v31
	v_pk_mul_f32 v[24:25], v[196:197], v[28:29]
	v_pk_mul_f32 v[22:23], v[174:175], v[26:27]
	v_fmac_f32_e32 v0, v30, v30
	v_cvt_pk_bf16_f32 v22, v22, v23
	v_cvt_pk_bf16_f32 v23, v24, v25
	v_cvt_pk_bf16_f32 v24, v36, v37
	v_cvt_pk_bf16_f32 v25, v34, v35
	global_store_dwordx4 v58, v[22:25], s[26:27] offset:256
	s_nop 1
	v_mul_f32_e32 v23, v27, v27
	v_mul_f32_e32 v24, v29, v29
	v_mul_f32_e32 v22, v33, v33
	v_fmac_f32_e32 v23, v26, v26
	v_fmac_f32_e32 v24, v28, v28
	v_fmac_f32_e32 v22, v32, v32
	v_add_f32_e32 v23, v23, v24
	v_add_f32_e32 v22, v22, v23
	v_add_f32_e32 v0, v0, v22
	v_add_f32_e32 v0, v50, v0
	ds_bpermute_b32 v22, v229, v0
	s_waitcnt lgkmcnt(0)
	v_add_f32_e32 v0, v0, v22
	ds_bpermute_b32 v22, v228, v0
	s_and_saveexec_b64 s[2:3], s[8:9]
	s_cbranch_execz .LBB0_1101
	s_waitcnt lgkmcnt(0)
	v_add_f32_e32 v0, v0, v22
	v_mul_f32_e32 v0, 0x4b800000, v0
	v_trunc_f32_e32 v0, v0
	v_mul_f32_e32 v22, 0x2f800000, v0
	v_floor_f32_e32 v23, v22
	v_fmac_f32_e32 v0, 0xcf800000, v23
	v_cvt_u32_f32_e32 v22, v0
	v_cvt_u32_f32_e32 v23, v23
	global_atomic_add_x2 v[134:135], v[22:23], off offset:1280
; #define PG8_GPTR(p) ((__attribute__((address_space(1))) char*)(p))
;     __device__ __forceinline__ void operator()(const f32x4 (&acc)[2][2][4][2], const Unit& u, int wr, int wc, int fr, int fq) const {
;     ...
;         if constexpr (GN) { ssq_t sc_[8];
; #pragma unroll
;             for (int i = 0; i < 8; ++i) sc_[i] = gsc[u.pm * BM + wr * 64 + fr + (i >> 2) * HALF + (i & 3) * 16];
; #pragma unroll
;             for (int i = 0; i < 8; ++i) rc[i] = 1.0f / sqrtf(ssq_val(sc_[i]) * (1.0f / 256.0f) + EPS); }
;     ...
;             for (int mm = 0; mm < 2; ++mm) {
;                 const int m = mp + mm;
;                 const int row = u.pm * BM + ai * HALF + wr * 64 + m * 16 + fr; float q = 0.f;
; #pragma unroll
;                 for (int bj = 0; bj < 2; ++bj) {
;                     const unsigned offb = (unsigned)(row * DM + col0 + bj * HALF) * 2u;
;                     const u32x4 bw = bv[mm][bj];
;                     const f32x4 b0 = (f32x4){__uint_as_float(bw.x << 16), __uint_as_float(bw.x & 0xffff0000u), __uint_as_float(bw.y << 16), __uint_as_float(bw.y & 0xffff0000u)};
;                     const f32x4 b1 = (f32x4){__uint_as_float(bw.z << 16), __uint_as_float(bw.z & 0xffff0000u), __uint_as_float(bw.w << 16), __uint_as_float(bw.w & 0xffff0000u)};
;                     f32x4 a0 = acc[ai][bj][m][0], a1 = acc[ai][bj][m][1]; if constexpr (GN) { a0 *= rc[ai * 4 + m]; a1 *= rc[ai * 4 + m]; }
;                     const f32x4 o0 = b0 + g[bj][0] * a0, o1 = b1 + g[bj][1] * a1;
;                     u32x4 wo; wo.x = cvt_pk_bf16(o0[0], o0[1]); wo.y = cvt_pk_bf16(o0[2], o0[3]); wo.z = cvt_pk_bf16(o1[0], o1[1]); wo.w = cvt_pk_bf16(o1[2], o1[3]);
;                     *(gs_u32x4*)(PG8_GPTR(out) + offb) = wo;
;                     if (xg) {
;                         const f32x4 h0 = o0 * cf[bj][0], h1 = o1 * cf[bj][1];
;                         u32x4 w; w.x = cvt_pk_bf16(h0[0], h0[1]); w.y = cvt_pk_bf16(h0[2], h0[3]); w.z = cvt_pk_bf16(h1[0], h1[1]); w.w = cvt_pk_bf16(h1[2], h1[3]);
;                         *(gs_u32x4*)(PG8_GPTR(xg) + offb) = w;
;                         q += (o0[0] * o0[0] + o0[1] * o0[1]) + (o0[2] * o0[2] + o0[3] * o0[3]) + (o1[0] * o1[0] + o1[1] * o1[1]) + (o1[2] * o1[2] + o1[3] * o1[3]);
;                     }
;                 }
;                 if (xg) ssq_put(ssq, row, q, fr, fq);
;             }
.LBB0_1101:
	s_or_b64 exec, exec, s[2:3]
	v_ffbh_u32_e32 v0, v3
	v_min_u32_e32 v0, 32, v0
	v_lshlrev_b64 v[2:3], v0, v[2:3]
	v_min_u32_e32 v2, 1, v2
	v_or_b32_e32 v2, v3, v2
	v_cvt_f32_u32_e32 v2, v2
	v_sub_u32_e32 v0, 32, v0
	v_and_b32_e32 v25, 0xffff0000, v44
	v_lshlrev_b32_e32 v26, 16, v45
	v_ldexp_f32 v0, v2, v0
	v_mul_f32_e32 v0, 0x33800000, v0
	v_fmamk_f32 v0, v0, 0x3b800000, v226
	v_and_b32_e32 v27, 0xffff0000, v45
	s_nop 0
	s_waitcnt lgkmcnt(0)
	s_mov_b32 s2, 0x58000
	v_add3_u32 v28, v136, v230, s2
	v_add_u32_e32 v241, s2, v240
	v_rsq_f32_e32 v0, v0
	s_nop 0
	v_lshlrev_b32_e32 v2, 16, v42
	v_and_b32_e32 v3, 0xffff0000, v42
	v_lshlrev_b32_e32 v22, 16, v43
	v_and_b32_e32 v23, 0xffff0000, v43
	v_lshlrev_b32_e32 v24, 16, v44
	v_pk_mul_f32 v[18:19], v[18:19], v[0:1] op_sel_hi:[1,0]
	v_pk_mul_f32 v[20:21], v[20:21], v[0:1] op_sel_hi:[1,0]
	v_pk_mul_f32 v[12:13], v[12:13], v[0:1] op_sel_hi:[1,0]
	v_pk_mul_f32 v[14:15], v[14:15], v[0:1] op_sel_hi:[1,0]
	v_pk_fma_f32 v[20:21], v[84:85], v[20:21], v[22:23]
	v_pk_fma_f32 v[2:3], v[82:83], v[18:19], v[2:3]
	v_pk_fma_f32 v[22:23], v[78:79], v[12:13], v[24:25]
	v_cvt_pk_bf16_f32 v12, v2, v3
	v_cvt_pk_bf16_f32 v13, v20, v21
	v_pk_fma_f32 v[18:19], v[80:81], v[14:15], v[26:27]
	v_cvt_pk_bf16_f32 v14, v22, v23
	v_pk_mul_f32 v[26:27], v[202:203], v[22:23]
	v_cvt_pk_bf16_f32 v15, v18, v19
	global_store_dwordx4 v241, v[12:15], s[24:25] nt
	v_pk_mul_f32 v[24:25], v[198:199], v[18:19]
	v_pk_mul_f32 v[8:9], v[8:9], v[0:1] op_sel_hi:[1,0]
	v_pk_mul_f32 v[12:13], v[204:205], v[2:3]
	v_mul_f32_e32 v3, v3, v3
	v_fmac_f32_e32 v3, v2, v2
	v_mul_f32_e32 v2, v21, v21
	v_fmac_f32_e32 v2, v20, v20
	v_add_f32_e32 v2, v3, v2
	v_mul_f32_e32 v3, v23, v23
	v_fmac_f32_e32 v3, v22, v22
	v_pk_mul_f32 v[14:15], v[200:201], v[20:21]
	v_add_f32_e32 v2, v3, v2
	v_mul_f32_e32 v3, v19, v19
	v_cvt_pk_bf16_f32 v12, v12, v13
	v_cvt_pk_bf16_f32 v13, v14, v15
	v_cvt_pk_bf16_f32 v14, v26, v27
	v_cvt_pk_bf16_f32 v15, v24, v25
	v_fmac_f32_e32 v3, v18, v18
	global_store_dwordx4 v28, v[12:15], s[26:27]
	v_add_f32_e32 v20, v3, v2
	v_lshlrev_b32_e32 v2, 16, v38
	v_and_b32_e32 v3, 0xffff0000, v38
	v_lshlrev_b32_e32 v12, 16, v39
	v_and_b32_e32 v13, 0xffff0000, v39
	v_lshlrev_b32_e32 v14, 16, v40
	v_and_b32_e32 v15, 0xffff0000, v40
	v_pk_mul_f32 v[10:11], v[10:11], v[0:1] op_sel_hi:[1,0]
	v_pk_mul_f32 v[4:5], v[4:5], v[0:1] op_sel_hi:[1,0]
	v_lshlrev_b32_e32 v18, 16, v41
	v_and_b32_e32 v19, 0xffff0000, v41
	v_pk_mul_f32 v[6:7], v[6:7], v[0:1] op_sel_hi:[1,0]
	v_pk_fma_f32 v[10:11], v[76:77], v[10:11], v[12:13]
	v_pk_fma_f32 v[8:9], v[74:75], v[8:9], v[2:3]
	v_pk_fma_f32 v[12:13], v[70:71], v[4:5], v[14:15]
	v_cvt_pk_bf16_f32 v2, v8, v9
	v_cvt_pk_bf16_f32 v3, v10, v11
	v_pk_fma_f32 v[6:7], v[72:73], v[6:7], v[18:19]
	v_cvt_pk_bf16_f32 v4, v12, v13
	v_pk_mul_f32 v[14:15], v[196:197], v[10:11]
	v_cvt_pk_bf16_f32 v5, v6, v7
	global_store_dwordx4 v241, v[2:5], s[24:25] offset:1024 nt
	v_mul_f32_e32 v0, v7, v7
	v_fmac_f32_e32 v0, v6, v6
	v_mul_f32_e32 v3, v9, v9
	v_mul_f32_e32 v4, v11, v11
	v_mul_f32_e32 v2, v13, v13
	v_fmac_f32_e32 v3, v8, v8
	v_fmac_f32_e32 v4, v10, v10
	v_fmac_f32_e32 v2, v12, v12
	v_add_f32_e32 v3, v3, v4
	v_add_f32_e32 v2, v2, v3
	v_add_f32_e32 v0, v0, v2
	v_add_f32_e32 v0, v20, v0
	ds_bpermute_b32 v5, v229, v0
	v_pk_mul_f32 v[2:3], v[174:175], v[8:9]
	v_pk_mul_f32 v[8:9], v[176:177], v[6:7]
	v_cvt_pk_bf16_f32 v4, v2, v3
	v_pk_mul_f32 v[6:7], v[194:195], v[12:13]
	s_waitcnt lgkmcnt(0)
	v_add_f32_e32 v0, v0, v5
	ds_bpermute_b32 v2, v228, v0
	v_cvt_pk_bf16_f32 v5, v14, v15
	v_cvt_pk_bf16_f32 v6, v6, v7
	v_cvt_pk_bf16_f32 v7, v8, v9
	global_store_dwordx4 v28, v[4:7], s[26:27] offset:256
	s_and_saveexec_b64 s[2:3], s[8:9]
	s_cbranch_execz .LBB0_1103
	s_waitcnt lgkmcnt(0)
	v_add_f32_e32 v0, v0, v2
	v_mul_f32_e32 v0, 0x4b800000, v0
	v_trunc_f32_e32 v0, v0
	v_mul_f32_e32 v2, 0x2f800000, v0
	v_floor_f32_e32 v3, v2
	v_fmac_f32_e32 v0, 0xcf800000, v3
	v_cvt_u32_f32_e32 v2, v0
	v_cvt_u32_f32_e32 v3, v3
	global_atomic_add_x2 v[134:135], v[2:3], off offset:1408

; #define PG8_GCPTR(p) ((__attribute__((address_space(1))) const char*)(p))
;     __device__ __forceinline__ void operator()(const f32x4 (&acc)[2][2][4][2], const Unit& u, int wr, int wc, int fr, int fq) const {
;     ...
;         const int col0 = u.pn * BM + wc * 32 + 8 * fq; const int b = (u.pm * BM) >> 12;
;         const float* gp = gate + (size_t)b * NMOD + col0; const float* sp = sc + (size_t)b * NMOD + col0;
;         f32x4 g[2][2], cf[2][2];
; #pragma unroll
;         for (int bj = 0; bj < 2; ++bj) {
;             g[bj][0] = *(const f32x4*)(gp + bj * HALF); g[bj][1] = *(const f32x4*)(gp + bj * HALF + 4);
;             const f32x4 n0 = *(const f32x4*)(nw + col0 + bj * HALF), n1 = *(const f32x4*)(nw + col0 + bj * HALF + 4);
;             const f32x4 c0 = *(const f32x4*)(sp + bj * HALF), c1 = *(const f32x4*)(sp + bj * HALF + 4);
;             cf[bj][0] = n0 * (c0 + 1.0f); cf[bj][1] = n1 * (c1 + 1.0f);
;         }
; #pragma unroll
;         for (int ai = 0; ai < 2; ++ai)
; #pragma unroll
;         for (int mp = 0; mp < 4; mp += 2) {
;             u32x4 bv[2][2];
; #pragma unroll
;             for (int mm = 0; mm < 2; ++mm)
; #pragma unroll
;                 for (int bj = 0; bj < 2; ++bj)
;                     bv[mm][bj] = *(gl_u32x4*)(PG8_GCPTR(base) + (unsigned)((u.pm * BM + ai * HALF + wr * 64 + (mp + mm) * 16 + fr) * DM + col0 + bj * HALF) * 2u);
; #pragma unroll
;             for (int mm = 0; mm < 2; ++mm) {
;                 const int m = mp + mm;
;                 const int row = u.pm * BM + ai * HALF + wr * 64 + m * 16 + fr; float q = 0.f;
; #pragma unroll
;                 for (int bj = 0; bj < 2; ++bj) {
;                     const unsigned offb = (unsigned)(row * DM + col0 + bj * HALF) * 2u;
;                     const u32x4 bw = bv[mm][bj];
;                     const f32x4 b0 = (f32x4){__uint_as_float(bw.x << 16), __uint_as_float(bw.x & 0xffff0000u), __uint_as_float(bw.y << 16), __uint_as_float(bw.y & 0xffff0000u)};
;                     const f32x4 b1 = (f32x4){__uint_as_float(bw.z << 16), __uint_as_float(bw.z & 0xffff0000u), __uint_as_float(bw.w << 16), __uint_as_float(bw.w & 0xffff0000u)};
;                     f32x4 a0 = acc[ai][bj][m][0], a1 = acc[ai][bj][m][1]; if constexpr (GN) { a0 *= rc[ai * 4 + m]; a1 *= rc[ai * 4 + m]; }
;                     const f32x4 o0 = b0 + g[bj][0] * a0, o1 = b1 + g[bj][1] * a1;
.LBB0_1246:
	v_mbcnt_lo_u32_b32 v0, -1, 0
	v_mbcnt_hi_u32_b32 v0, -1, v0
	s_lshl_b32 s2, s88, 8
	v_bfe_u32 v205, v0, 4, 2
	v_and_b32_e32 v219, 15, v0
	v_lshl_or_b32 v0, v205, 3, s2
	s_ashr_i32 s2, s87, 4
	v_or_b32_e32 v174, s51, v0
	s_mul_i32 s5, s2, 0x6000
	s_mul_hi_i32 s4, s2, 0x6000
	s_add_u32 s2, s67, s5
	v_ashrrev_i32_e32 v175, 31, v174
	s_addc_u32 s3, s73, s4
	v_lshlrev_b64 v[62:63], 2, v[174:175]
	v_lshl_add_u64 v[158:159], s[2:3], 0, v[62:63]
	s_add_u32 s2, s48, s5
	s_addc_u32 s3, s49, s4
	v_lshl_add_u64 v[162:163], s[2:3], 0, v[62:63]
	v_lshl_add_u64 v[164:165], s[18:19], 0, v[62:63]
	global_load_dwordx4 v[74:77], v[158:159], off
	global_load_dwordx4 v[70:73], v[158:159], off offset:16
	global_load_dwordx4 v[62:65], v[164:165], off offset:16
	global_load_dwordx4 v[66:69], v[164:165], off
	global_load_dwordx4 v[150:153], v[162:163], off
	global_load_dwordx4 v[154:157], v[162:163], off offset:16
	s_lshl_b32 s2, s87, 8
	s_add_i32 s2, s2, s50
	v_or_b32_e32 v204, s2, v219
	v_lshlrev_b32_e32 v217, 1, v174
	v_lshlrev_b32_e32 v218, 11, v204
	v_add_u32_e32 v0, v217, v218
	v_and_b32_e32 v240, 0xffff8000, v0
	v_bfe_u32 v241, v0, 11, 4
	v_lshl_or_b32 v240, v241, 6, v240
	v_bfe_u32 v241, v0, 9, 2
	v_lshl_or_b32 v240, v241, 13, v240
	v_bfe_u32 v241, v0, 6, 2
	v_lshl_or_b32 v240, v241, 11, v240
	v_and_b32_e32 v241, 48, v0
	v_or_b32_e32 v240, v240, v241
	s_andn2_b64 vcc, exec, s[26:27]
	v_lshl_add_u64 v[214:215], s[12:13], 0, v[0:1]
	s_waitcnt vmcnt(0) lgkmcnt(0)
	v_pk_add_f32 v[152:153], v[152:153], 1.0 op_sel_hi:[1,0]
	v_pk_add_f32 v[150:151], v[150:151], 1.0 op_sel_hi:[1,0]
	v_pk_mul_f32 v[210:211], v[68:69], v[152:153]
	v_pk_mul_f32 v[212:213], v[66:67], v[150:151]
	v_pk_add_f32 v[66:67], v[156:157], 1.0 op_sel_hi:[1,0]
	v_pk_add_f32 v[68:69], v[154:155], 1.0 op_sel_hi:[1,0]
	v_pk_mul_f32 v[206:207], v[64:65], v[66:67]
	v_pk_mul_f32 v[208:209], v[62:63], v[68:69]
	global_load_dwordx4 v[66:69], v[158:159], off offset:512
	global_load_dwordx4 v[62:65], v[158:159], off offset:528
	s_nop 0
	global_load_dwordx4 v[158:161], v[164:165], off offset:528
	global_load_dwordx4 v[166:169], v[164:165], off offset:512
	global_load_dwordx4 v[170:173], v[162:163], off offset:512
	s_nop 0
	global_load_dwordx4 v[162:165], v[162:163], off offset:528
	s_nop 0
	global_load_dwordx4 v[178:181], v240, s[20:21] nt
	global_load_dwordx4 v[174:177], v240, s[20:21] offset:1024 nt
	v_add_u32_e32 v150, 0x8000, v240
	global_load_dwordx4 v[154:157], v150, s[20:21] nt
	s_nop 0
	global_load_dwordx4 v[150:153], v150, s[20:21] offset:1024 nt
	s_waitcnt vmcnt(0)
	v_lshlrev_b32_e32 v182, 16, v178
	v_and_b32_e32 v183, 0xffff0000, v178
	v_lshlrev_b32_e32 v178, 16, v179
	v_and_b32_e32 v179, 0xffff0000, v179
	v_lshlrev_b32_e32 v184, 16, v180
	v_and_b32_e32 v185, 0xffff0000, v180
	v_lshlrev_b32_e32 v180, 16, v181
	v_and_b32_e32 v181, 0xffff0000, v181
	v_pk_fma_f32 v[148:149], v[148:149], v[76:77], v[178:179]
	v_pk_fma_f32 v[146:147], v[146:147], v[74:75], v[182:183]
	v_pk_fma_f32 v[144:145], v[144:145], v[72:73], v[180:181]
	v_cvt_pk_bf16_f32 v178, v146, v147
	v_pk_fma_f32 v[142:143], v[142:143], v[70:71], v[184:185]
	v_cvt_pk_bf16_f32 v179, v148, v149
	s_nop 0
	v_cvt_pk_bf16_f32 v180, v142, v143
	v_cvt_pk_bf16_f32 v181, v144, v145
	global_store_dwordx4 v240, v[178:181], s[22:23] nt
	s_nop 1
	v_cndmask_b32_e64 v178, 0, 1, s[26:27]
	v_cmp_ne_u32_e64 s[8:9], 1, v178
	s_cbranch_vccnz .LBB0_1248
	v_pk_mul_f32 v[178:179], v[212:213], v[146:147]
	v_pk_mul_f32 v[180:181], v[210:211], v[148:149]
	v_cvt_pk_bf16_f32 v178, v178, v179
	v_pk_mul_f32 v[148:149], v[148:149], v[148:149]
	v_cvt_pk_bf16_f32 v179, v180, v181
	v_pk_mul_f32 v[146:147], v[146:147], v[146:147]
	v_pk_mul_f32 v[182:183], v[206:207], v[144:145]
	v_pk_mul_f32 v[184:185], v[208:209], v[142:143]
	v_pk_mul_f32 v[144:145], v[144:145], v[144:145]
	v_cvt_pk_bf16_f32 v180, v184, v185
	v_cvt_pk_bf16_f32 v181, v182, v183
	global_store_dwordx4 v[214:215], v[178:181], off
	v_pk_mul_f32 v[142:143], v[142:143], v[142:143]
	s_nop 0
	v_mov_b32_e32 v178, v146
	v_mov_b32_e32 v179, v149
	v_pk_mov_b32 v[146:147], v[146:147], v[148:149] op_sel:[1,0]
	v_mov_b32_e32 v148, v144
	v_pk_add_f32 v[146:147], v[146:147], v[178:179]
	v_mov_b32_e32 v149, v142
	v_mov_b32_e32 v142, v145
	v_pk_add_f32 v[142:143], v[148:149], v[142:143]
	v_add_f32_e32 v144, v146, v147
	v_add_f32_e32 v143, v143, v144
	v_add_f32_e32 v227, v142, v143
	s_branch .LBB0_1249

; __device__ __forceinline__ unsigned cvt_pk_bf16(float lo, float hi) { unsigned r; asm volatile("v_cvt_pk_bf16_f32 %0, %1, %2" : "=v"(r) : "v"(lo), "v"(hi)); return r; }
; #define PG8_GPTR(p) ((__attribute__((address_space(1))) char*)(p))
;     __device__ __forceinline__ void operator()(const f32x4 (&acc)[2][2][4][2], const Unit& u, int wr, int wc, int fr, int fq) const {
;     ...
;             for (int mm = 0; mm < 2; ++mm) {
;                 const int m = mp + mm;
;                 const int row = u.pm * BM + ai * HALF + wr * 64 + m * 16 + fr; float q = 0.f;
; #pragma unroll
;                 for (int bj = 0; bj < 2; ++bj) {
;                     const unsigned offb = (unsigned)(row * DM + col0 + bj * HALF) * 2u;
;                     const u32x4 bw = bv[mm][bj];
;                     const f32x4 b0 = (f32x4){__uint_as_float(bw.x << 16), __uint_as_float(bw.x & 0xffff0000u), __uint_as_float(bw.y << 16), __uint_as_float(bw.y & 0xffff0000u)};
;                     const f32x4 b1 = (f32x4){__uint_as_float(bw.z << 16), __uint_as_float(bw.z & 0xffff0000u), __uint_as_float(bw.w << 16), __uint_as_float(bw.w & 0xffff0000u)};
;                     f32x4 a0 = acc[ai][bj][m][0], a1 = acc[ai][bj][m][1]; if constexpr (GN) { a0 *= rc[ai * 4 + m]; a1 *= rc[ai * 4 + m]; }
;                     const f32x4 o0 = b0 + g[bj][0] * a0, o1 = b1 + g[bj][1] * a1;
;                     u32x4 wo; wo.x = cvt_pk_bf16(o0[0], o0[1]); wo.y = cvt_pk_bf16(o0[2], o0[3]); wo.z = cvt_pk_bf16(o1[0], o1[1]); wo.w = cvt_pk_bf16(o1[2], o1[3]);
;                     *(gs_u32x4*)(PG8_GPTR(out) + offb) = wo;
;                     if (xg) {
;                         const f32x4 h0 = o0 * cf[bj][0], h1 = o1 * cf[bj][1];
;                         u32x4 w; w.x = cvt_pk_bf16(h0[0], h0[1]); w.y = cvt_pk_bf16(h0[2], h0[3]); w.z = cvt_pk_bf16(h1[0], h1[1]); w.w = cvt_pk_bf16(h1[2], h1[3]);
;                         *(gs_u32x4*)(PG8_GPTR(xg) + offb) = w;
;                         q += (o0[0] * o0[0] + o0[1] * o0[1]) + (o0[2] * o0[2] + o0[3] * o0[3]) + (o1[0] * o1[0] + o1[1] * o1[1]) + (o1[2] * o1[2] + o1[3] * o1[3]);
;                     }
;                 }
;                 if (xg) ssq_put(ssq, row, q, fr, fq);
;             }
.LBB0_1249:
	s_waitcnt lgkmcnt(0)
	v_pk_add_f32 v[142:143], v[172:173], 1.0 op_sel_hi:[1,0]
	v_pk_add_f32 v[144:145], v[170:171], 1.0 op_sel_hi:[1,0]
	v_pk_mul_f32 v[148:149], v[168:169], v[142:143]
	v_pk_mul_f32 v[142:143], v[166:167], v[144:145]
	v_pk_add_f32 v[144:145], v[164:165], 1.0 op_sel_hi:[1,0]
	v_pk_add_f32 v[146:147], v[162:163], 1.0 op_sel_hi:[1,0]
	v_pk_mul_f32 v[144:145], v[160:161], v[144:145]
	v_pk_mul_f32 v[146:147], v[158:159], v[146:147]
	v_lshlrev_b32_e32 v158, 6, v205
	v_lshlrev_b32_e32 v160, 2, v219
	s_movk_i32 s2, 0x80
	v_bitop3_b32 v159, v158, 64, v160 bitop3:0x36
	v_bitop3_b32 v158, v158, s2, v160 bitop3:0x36
	v_lshlrev_b32_e32 v160, 16, v174
	v_and_b32_e32 v161, 0xffff0000, v174
	v_lshlrev_b32_e32 v162, 16, v175
	v_and_b32_e32 v163, 0xffff0000, v175
	v_lshlrev_b32_e32 v164, 16, v176
	v_and_b32_e32 v165, 0xffff0000, v176
	v_lshlrev_b32_e32 v166, 16, v177
	v_and_b32_e32 v167, 0xffff0000, v177
	v_lshl_add_u64 v[178:179], s[22:23], 0, v[0:1]
	v_cmp_eq_u32_e64 s[10:11], 0, v205
	v_pk_fma_f32 v[140:141], v[140:141], v[68:69], v[162:163]
	v_pk_fma_f32 v[138:139], v[138:139], v[66:67], v[160:161]
	v_pk_fma_f32 v[136:137], v[136:137], v[64:65], v[166:167]
	v_pk_fma_f32 v[134:135], v[134:135], v[62:63], v[164:165]
	s_and_b64 vcc, exec, s[8:9]
	v_cvt_pk_bf16_f32 v160, v138, v139
	v_cvt_pk_bf16_f32 v161, v140, v141
	v_cvt_pk_bf16_f32 v162, v134, v135
	v_cvt_pk_bf16_f32 v163, v136, v137
	global_store_dwordx4 v240, v[160:163], s[22:23] offset:1024 nt
	s_cbranch_vccnz .LBB0_1253
	s_nop 0
	v_pk_mul_f32 v[160:161], v[148:149], v[140:141]
	v_mul_f32_e32 v164, v139, v139
	v_mul_f32_e32 v141, v141, v141
	v_mul_f32_e32 v163, v135, v135
	v_fmac_f32_e32 v164, v138, v138
	v_fmac_f32_e32 v141, v140, v140
	v_mul_f32_e32 v162, v137, v137
	v_fmac_f32_e32 v163, v134, v134
	v_add_f32_e32 v140, v164, v141
	v_fmac_f32_e32 v162, v136, v136
	v_add_f32_e32 v140, v163, v140
	v_add_f32_e32 v140, v162, v140
	v_add_f32_e32 v164, v140, v227
	ds_bpermute_b32 v165, v159, v164
	v_pk_mul_f32 v[162:163], v[146:147], v[134:135]
	v_pk_mul_f32 v[138:139], v[142:143], v[138:139]
	v_pk_mul_f32 v[140:141], v[144:145], v[136:137]
	v_cvt_pk_bf16_f32 v136, v138, v139
	s_waitcnt lgkmcnt(0)
	v_add_f32_e32 v134, v164, v165
	ds_bpermute_b32 v135, v158, v134
	v_cvt_pk_bf16_f32 v137, v160, v161
	v_cvt_pk_bf16_f32 v138, v162, v163
	v_cvt_pk_bf16_f32 v139, v140, v141
	global_store_dwordx4 v[214:215], v[136:139], off offset:256
	s_and_saveexec_b64 s[2:3], s[10:11]
	s_cbranch_execz .LBB0_1252
	s_waitcnt lgkmcnt(0)
	v_add_f32_e32 v134, v134, v135
	v_mul_f32_e32 v134, 0x4b800000, v134
	v_trunc_f32_e32 v134, v134
	v_mul_f32_e32 v135, 0x2f800000, v134
	v_floor_f32_e32 v135, v135
	v_fmac_f32_e32 v134, 0xcf800000, v135
	v_cvt_u32_f32_e32 v134, v134
	v_cvt_u32_f32_e32 v135, v135
	v_ashrrev_i32_e32 v205, 31, v204
	v_lshl_add_u64 v[136:137], v[204:205], 3, s[16:17]
	global_atomic_add_x2 v[136:137], v[134:135], off

; __device__ __forceinline__ unsigned cvt_pk_bf16(float lo, float hi) { unsigned r; asm volatile("v_cvt_pk_bf16_f32 %0, %1, %2" : "=v"(r) : "v"(lo), "v"(hi)); return r; }
; #define PG8_GPTR(p) ((__attribute__((address_space(1))) char*)(p))
;     __device__ __forceinline__ void operator()(const f32x4 (&acc)[2][2][4][2], const Unit& u, int wr, int wc, int fr, int fq) const {
;     ...
;             for (int mm = 0; mm < 2; ++mm) {
;                 const int m = mp + mm;
;                 const int row = u.pm * BM + ai * HALF + wr * 64 + m * 16 + fr; float q = 0.f;
; #pragma unroll
;                 for (int bj = 0; bj < 2; ++bj) {
;                     const unsigned offb = (unsigned)(row * DM + col0 + bj * HALF) * 2u;
;                     const u32x4 bw = bv[mm][bj];
;                     const f32x4 b0 = (f32x4){__uint_as_float(bw.x << 16), __uint_as_float(bw.x & 0xffff0000u), __uint_as_float(bw.y << 16), __uint_as_float(bw.y & 0xffff0000u)};
;                     const f32x4 b1 = (f32x4){__uint_as_float(bw.z << 16), __uint_as_float(bw.z & 0xffff0000u), __uint_as_float(bw.w << 16), __uint_as_float(bw.w & 0xffff0000u)};
;                     f32x4 a0 = acc[ai][bj][m][0], a1 = acc[ai][bj][m][1]; if constexpr (GN) { a0 *= rc[ai * 4 + m]; a1 *= rc[ai * 4 + m]; }
;                     const f32x4 o0 = b0 + g[bj][0] * a0, o1 = b1 + g[bj][1] * a1;
;                     u32x4 wo; wo.x = cvt_pk_bf16(o0[0], o0[1]); wo.y = cvt_pk_bf16(o0[2], o0[3]); wo.z = cvt_pk_bf16(o1[0], o1[1]); wo.w = cvt_pk_bf16(o1[2], o1[3]);
;                     *(gs_u32x4*)(PG8_GPTR(out) + offb) = wo;
;                     if (xg) {
;                         const f32x4 h0 = o0 * cf[bj][0], h1 = o1 * cf[bj][1];
;                         u32x4 w; w.x = cvt_pk_bf16(h0[0], h0[1]); w.y = cvt_pk_bf16(h0[2], h0[3]); w.z = cvt_pk_bf16(h1[0], h1[1]); w.w = cvt_pk_bf16(h1[2], h1[3]);
;                         *(gs_u32x4*)(PG8_GPTR(xg) + offb) = w;
;                         q += (o0[0] * o0[0] + o0[1] * o0[1]) + (o0[2] * o0[2] + o0[3] * o0[3]) + (o1[0] * o1[0] + o1[1] * o1[1]) + (o1[2] * o1[2] + o1[3] * o1[3]);
;                     }
;                 }
;                 if (xg) ssq_put(ssq, row, q, fr, fq);
;             }
.LBB0_1253:
	s_mov_b32 s2, 0x8000
	v_add3_u32 v134, v217, v218, s2
	v_add_u32_e32 v241, s2, v240
	v_lshlrev_b32_e32 v136, 16, v154
	v_and_b32_e32 v137, 0xffff0000, v154
	v_lshlrev_b32_e32 v138, 16, v155
	v_and_b32_e32 v139, 0xffff0000, v155
	v_lshlrev_b32_e32 v140, 16, v156
	v_and_b32_e32 v141, 0xffff0000, v156
	v_lshlrev_b32_e32 v154, 16, v157
	v_and_b32_e32 v155, 0xffff0000, v157
	s_waitcnt lgkmcnt(0)
	v_mov_b32_e32 v135, v1
	v_pk_fma_f32 v[132:133], v[132:133], v[76:77], v[138:139]
	v_pk_fma_f32 v[130:131], v[130:131], v[74:75], v[136:137]
	v_pk_fma_f32 v[128:129], v[128:129], v[72:73], v[154:155]
	v_pk_fma_f32 v[136:137], v[126:127], v[70:71], v[140:141]
	s_and_b64 vcc, exec, s[8:9]
	v_lshl_add_u64 v[126:127], s[12:13], 0, v[134:135]
	v_cvt_pk_bf16_f32 v138, v130, v131
	v_cvt_pk_bf16_f32 v139, v132, v133
	v_cvt_pk_bf16_f32 v140, v136, v137
	v_cvt_pk_bf16_f32 v141, v128, v129
	global_store_dwordx4 v241, v[138:141], s[22:23] nt
	s_cbranch_vccnz .LBB0_1255
	s_nop 0
	v_pk_mul_f32 v[138:139], v[212:213], v[130:131]
	v_pk_mul_f32 v[140:141], v[210:211], v[132:133]
	v_cvt_pk_bf16_f32 v138, v138, v139
	v_pk_mul_f32 v[132:133], v[132:133], v[132:133]
	v_cvt_pk_bf16_f32 v139, v140, v141
	v_pk_mul_f32 v[130:131], v[130:131], v[130:131]
	v_pk_mul_f32 v[154:155], v[206:207], v[128:129]
	v_pk_mul_f32 v[156:157], v[208:209], v[136:137]
	v_pk_mul_f32 v[128:129], v[128:129], v[128:129]
	v_cvt_pk_bf16_f32 v140, v156, v157
	v_cvt_pk_bf16_f32 v141, v154, v155
	global_store_dwordx4 v[126:127], v[138:141], off
	s_nop 1
	v_mov_b32_e32 v138, v130
	v_mov_b32_e32 v139, v133
	v_pk_mov_b32 v[130:131], v[130:131], v[132:133] op_sel:[1,0]
	v_pk_mul_f32 v[132:133], v[136:137], v[136:137]
	v_pk_add_f32 v[130:131], v[130:131], v[138:139]
	v_mov_b32_e32 v136, v128
	v_mov_b32_e32 v137, v132
	v_mov_b32_e32 v132, v129
	v_pk_add_f32 v[128:129], v[136:137], v[132:133]
	v_add_f32_e32 v130, v130, v131
	v_add_f32_e32 v129, v129, v130
	v_add_f32_e32 v128, v128, v129
	s_branch .LBB0_1256

; __device__ __forceinline__ unsigned cvt_pk_bf16(float lo, float hi) { unsigned r; asm volatile("v_cvt_pk_bf16_f32 %0, %1, %2" : "=v"(r) : "v"(lo), "v"(hi)); return r; }
; #define PG8_GPTR(p) ((__attribute__((address_space(1))) char*)(p))
;     __device__ __forceinline__ void operator()(const f32x4 (&acc)[2][2][4][2], const Unit& u, int wr, int wc, int fr, int fq) const {
;     ...
;             for (int mm = 0; mm < 2; ++mm) {
;                 const int m = mp + mm;
;                 const int row = u.pm * BM + ai * HALF + wr * 64 + m * 16 + fr; float q = 0.f;
; #pragma unroll
;                 for (int bj = 0; bj < 2; ++bj) {
;                     const unsigned offb = (unsigned)(row * DM + col0 + bj * HALF) * 2u;
;                     const u32x4 bw = bv[mm][bj];
;                     const f32x4 b0 = (f32x4){__uint_as_float(bw.x << 16), __uint_as_float(bw.x & 0xffff0000u), __uint_as_float(bw.y << 16), __uint_as_float(bw.y & 0xffff0000u)};
;                     const f32x4 b1 = (f32x4){__uint_as_float(bw.z << 16), __uint_as_float(bw.z & 0xffff0000u), __uint_as_float(bw.w << 16), __uint_as_float(bw.w & 0xffff0000u)};
;                     f32x4 a0 = acc[ai][bj][m][0], a1 = acc[ai][bj][m][1]; if constexpr (GN) { a0 *= rc[ai * 4 + m]; a1 *= rc[ai * 4 + m]; }
;                     const f32x4 o0 = b0 + g[bj][0] * a0, o1 = b1 + g[bj][1] * a1;
;                     u32x4 wo; wo.x = cvt_pk_bf16(o0[0], o0[1]); wo.y = cvt_pk_bf16(o0[2], o0[3]); wo.z = cvt_pk_bf16(o1[0], o1[1]); wo.w = cvt_pk_bf16(o1[2], o1[3]);
;                     *(gs_u32x4*)(PG8_GPTR(out) + offb) = wo;
;                     if (xg) {
;                         const f32x4 h0 = o0 * cf[bj][0], h1 = o1 * cf[bj][1];
;                         u32x4 w; w.x = cvt_pk_bf16(h0[0], h0[1]); w.y = cvt_pk_bf16(h0[2], h0[3]); w.z = cvt_pk_bf16(h1[0], h1[1]); w.w = cvt_pk_bf16(h1[2], h1[3]);
;                         *(gs_u32x4*)(PG8_GPTR(xg) + offb) = w;
;                         q += (o0[0] * o0[0] + o0[1] * o0[1]) + (o0[2] * o0[2] + o0[3] * o0[3]) + (o1[0] * o1[0] + o1[1] * o1[1]) + (o1[2] * o1[2] + o1[3] * o1[3]);
;                     }
;                 }
;                 if (xg) ssq_put(ssq, row, q, fr, fq);
;             }
.LBB0_1256:
	v_lshlrev_b32_e32 v130, 16, v150
	v_and_b32_e32 v131, 0xffff0000, v150
	v_lshlrev_b32_e32 v132, 16, v151
	v_and_b32_e32 v133, 0xffff0000, v151
	v_lshlrev_b32_e32 v136, 16, v152
	v_and_b32_e32 v137, 0xffff0000, v152
	v_lshlrev_b32_e32 v138, 16, v153
	v_and_b32_e32 v139, 0xffff0000, v153
	v_lshl_add_u64 v[134:135], s[22:23], 0, v[134:135]
	v_pk_fma_f32 v[124:125], v[124:125], v[68:69], v[132:133]
	v_pk_fma_f32 v[122:123], v[122:123], v[66:67], v[130:131]
	v_pk_fma_f32 v[120:121], v[120:121], v[64:65], v[138:139]
	v_pk_fma_f32 v[118:119], v[118:119], v[62:63], v[136:137]
	s_and_b64 vcc, exec, s[8:9]
	v_cvt_pk_bf16_f32 v130, v122, v123
	v_cvt_pk_bf16_f32 v131, v124, v125
	v_cvt_pk_bf16_f32 v132, v118, v119
	v_cvt_pk_bf16_f32 v133, v120, v121
	global_store_dwordx4 v241, v[130:133], s[22:23] offset:1024 nt
	s_cbranch_vccnz .LBB0_1260
	s_nop 0
	v_pk_mul_f32 v[130:131], v[148:149], v[124:125]
	v_mul_f32_e32 v133, v123, v123
	v_mul_f32_e32 v125, v125, v125
	v_mul_f32_e32 v132, v119, v119
	v_fmac_f32_e32 v133, v122, v122
	v_fmac_f32_e32 v125, v124, v124
	v_mul_f32_e32 v129, v121, v121
	v_fmac_f32_e32 v132, v118, v118
	v_add_f32_e32 v124, v133, v125
	v_fmac_f32_e32 v129, v120, v120
	v_add_f32_e32 v124, v132, v124
	v_add_f32_e32 v124, v129, v124
	v_add_f32_e32 v132, v124, v128
	ds_bpermute_b32 v133, v159, v132
	v_pk_mul_f32 v[128:129], v[146:147], v[118:119]
	v_pk_mul_f32 v[122:123], v[142:143], v[122:123]
	v_pk_mul_f32 v[124:125], v[144:145], v[120:121]
	v_cvt_pk_bf16_f32 v120, v122, v123
	s_waitcnt lgkmcnt(0)
	v_add_f32_e32 v118, v132, v133
	ds_bpermute_b32 v119, v158, v118
	v_cvt_pk_bf16_f32 v121, v130, v131
	v_cvt_pk_bf16_f32 v122, v128, v129
	v_cvt_pk_bf16_f32 v123, v124, v125
	global_store_dwordx4 v[126:127], v[120:123], off offset:256
	s_and_saveexec_b64 s[2:3], s[10:11]
	s_cbranch_execz .LBB0_1259
	s_waitcnt lgkmcnt(0)
	v_add_f32_e32 v118, v118, v119
	v_mul_f32_e32 v118, 0x4b800000, v118
	v_trunc_f32_e32 v118, v118
	v_mul_f32_e32 v119, 0x2f800000, v118
	v_floor_f32_e32 v119, v119
	v_fmac_f32_e32 v118, 0xcf800000, v119
	v_cvt_u32_f32_e32 v118, v118
	v_cvt_u32_f32_e32 v119, v119
	v_ashrrev_i32_e32 v205, 31, v204
	v_lshl_add_u64 v[120:121], v[204:205], 3, s[16:17]
	global_atomic_add_x2 v[120:121], v[118:119], off offset:128

; #define PG8_GPTR(p) ((__attribute__((address_space(1))) char*)(p))
;     __device__ __forceinline__ void operator()(const f32x4 (&acc)[2][2][4][2], const Unit& u, int wr, int wc, int fr, int fq) const {
;     ...
;             u32x4 bv[2][2];
; #pragma unroll
;             for (int mm = 0; mm < 2; ++mm)
; #pragma unroll
;                 for (int bj = 0; bj < 2; ++bj)
;                     bv[mm][bj] = *(gl_u32x4*)(PG8_GCPTR(base) + (unsigned)((u.pm * BM + ai * HALF + wr * 64 + (mp + mm) * 16 + fr) * DM + col0 + bj * HALF) * 2u);
; #pragma unroll
;             for (int mm = 0; mm < 2; ++mm) {
;                 const int m = mp + mm;
;                 const int row = u.pm * BM + ai * HALF + wr * 64 + m * 16 + fr; float q = 0.f;
; #pragma unroll
;                 for (int bj = 0; bj < 2; ++bj) {
;                     const unsigned offb = (unsigned)(row * DM + col0 + bj * HALF) * 2u;
;                     const u32x4 bw = bv[mm][bj];
;                     const f32x4 b0 = (f32x4){__uint_as_float(bw.x << 16), __uint_as_float(bw.x & 0xffff0000u), __uint_as_float(bw.y << 16), __uint_as_float(bw.y & 0xffff0000u)};
;                     const f32x4 b1 = (f32x4){__uint_as_float(bw.z << 16), __uint_as_float(bw.z & 0xffff0000u), __uint_as_float(bw.w << 16), __uint_as_float(bw.w & 0xffff0000u)};
;                     f32x4 a0 = acc[ai][bj][m][0], a1 = acc[ai][bj][m][1]; if constexpr (GN) { a0 *= rc[ai * 4 + m]; a1 *= rc[ai * 4 + m]; }
;                     const f32x4 o0 = b0 + g[bj][0] * a0, o1 = b1 + g[bj][1] * a1;
;                     u32x4 wo; wo.x = cvt_pk_bf16(o0[0], o0[1]); wo.y = cvt_pk_bf16(o0[2], o0[3]); wo.z = cvt_pk_bf16(o1[0], o1[1]); wo.w = cvt_pk_bf16(o1[2], o1[3]);
;                     *(gs_u32x4*)(PG8_GPTR(out) + offb) = wo;
;                     if (xg) {
;                         const f32x4 h0 = o0 * cf[bj][0], h1 = o1 * cf[bj][1];
;                         u32x4 w; w.x = cvt_pk_bf16(h0[0], h0[1]); w.y = cvt_pk_bf16(h0[2], h0[3]); w.z = cvt_pk_bf16(h1[0], h1[1]); w.w = cvt_pk_bf16(h1[2], h1[3]);
;                         *(gs_u32x4*)(PG8_GPTR(xg) + offb) = w;
;                         q += (o0[0] * o0[0] + o0[1] * o0[1]) + (o0[2] * o0[2] + o0[3] * o0[3]) + (o1[0] * o1[0] + o1[1] * o1[1]) + (o1[2] * o1[2] + o1[3] * o1[3]);
;                     }
;                 }
;                 if (xg) ssq_put(ssq, row, q, fr, fq);
;             }
.LBB0_1260:
	v_add_u32_e32 v118, 0x10000, v240
	global_load_dwordx4 v[132:135], v118, s[20:21] nt
	global_load_dwordx4 v[126:129], v118, s[20:21] offset:1024 nt
	v_add_u32_e32 v118, 0x18000, v240
	global_load_dwordx4 v[122:125], v118, s[20:21] nt
	s_waitcnt lgkmcnt(0)
	global_load_dwordx4 v[118:121], v118, s[20:21] offset:1024 nt
	s_mov_b32 s2, 0x10000
	v_add3_u32 v130, v217, v218, s2
	v_add_u32_e32 v241, s2, v240
	v_mov_b32_e32 v131, v1
	s_and_b64 vcc, exec, s[8:9]
	s_waitcnt vmcnt(0)
	v_lshlrev_b32_e32 v136, 16, v132
	v_and_b32_e32 v137, 0xffff0000, v132
	v_lshlrev_b32_e32 v132, 16, v133
	v_and_b32_e32 v133, 0xffff0000, v133
	v_lshlrev_b32_e32 v138, 16, v134
	v_and_b32_e32 v139, 0xffff0000, v134
	v_lshlrev_b32_e32 v134, 16, v135
	v_and_b32_e32 v135, 0xffff0000, v135
	v_pk_fma_f32 v[116:117], v[116:117], v[76:77], v[132:133]
	v_pk_fma_f32 v[114:115], v[114:115], v[74:75], v[136:137]
	v_pk_fma_f32 v[112:113], v[112:113], v[72:73], v[134:135]
	v_cvt_pk_bf16_f32 v132, v114, v115
	v_cvt_pk_bf16_f32 v133, v116, v117
	v_pk_fma_f32 v[110:111], v[110:111], v[70:71], v[138:139]
	s_nop 0
	v_cvt_pk_bf16_f32 v134, v110, v111
	v_cvt_pk_bf16_f32 v135, v112, v113
	global_store_dwordx4 v241, v[132:135], s[22:23] nt
	s_nop 1
	v_lshl_add_u64 v[132:133], s[12:13], 0, v[130:131]
	s_cbranch_vccnz .LBB0_1262
	v_pk_mul_f32 v[134:135], v[212:213], v[114:115]
	v_pk_mul_f32 v[136:137], v[210:211], v[116:117]
	v_cvt_pk_bf16_f32 v134, v134, v135
	v_pk_mul_f32 v[116:117], v[116:117], v[116:117]
	v_cvt_pk_bf16_f32 v135, v136, v137
	v_pk_mul_f32 v[114:115], v[114:115], v[114:115]
	v_pk_mul_f32 v[138:139], v[206:207], v[112:113]
	v_pk_mul_f32 v[140:141], v[208:209], v[110:111]
	v_pk_mul_f32 v[112:113], v[112:113], v[112:113]
	v_cvt_pk_bf16_f32 v136, v140, v141
	v_cvt_pk_bf16_f32 v137, v138, v139
	global_store_dwordx4 v[132:133], v[134:137], off
	v_pk_mul_f32 v[110:111], v[110:111], v[110:111]
	s_nop 0
	v_mov_b32_e32 v134, v114
	v_mov_b32_e32 v135, v117
	v_pk_mov_b32 v[114:115], v[114:115], v[116:117] op_sel:[1,0]
	v_mov_b32_e32 v116, v112
	v_pk_add_f32 v[114:115], v[114:115], v[134:135]
	v_mov_b32_e32 v117, v110
	v_mov_b32_e32 v110, v113
	v_pk_add_f32 v[110:111], v[116:117], v[110:111]
	v_add_f32_e32 v112, v114, v115
	v_add_f32_e32 v111, v111, v112
	v_add_f32_e32 v110, v110, v111
	s_branch .LBB0_1263

; __device__ __forceinline__ unsigned cvt_pk_bf16(float lo, float hi) { unsigned r; asm volatile("v_cvt_pk_bf16_f32 %0, %1, %2" : "=v"(r) : "v"(lo), "v"(hi)); return r; }
; #define PG8_GPTR(p) ((__attribute__((address_space(1))) char*)(p))
;     __device__ __forceinline__ void operator()(const f32x4 (&acc)[2][2][4][2], const Unit& u, int wr, int wc, int fr, int fq) const {
;     ...
;             for (int mm = 0; mm < 2; ++mm) {
;                 const int m = mp + mm;
;                 const int row = u.pm * BM + ai * HALF + wr * 64 + m * 16 + fr; float q = 0.f;
; #pragma unroll
;                 for (int bj = 0; bj < 2; ++bj) {
;                     const unsigned offb = (unsigned)(row * DM + col0 + bj * HALF) * 2u;
;                     const u32x4 bw = bv[mm][bj];
;                     const f32x4 b0 = (f32x4){__uint_as_float(bw.x << 16), __uint_as_float(bw.x & 0xffff0000u), __uint_as_float(bw.y << 16), __uint_as_float(bw.y & 0xffff0000u)};
;                     const f32x4 b1 = (f32x4){__uint_as_float(bw.z << 16), __uint_as_float(bw.z & 0xffff0000u), __uint_as_float(bw.w << 16), __uint_as_float(bw.w & 0xffff0000u)};
;                     f32x4 a0 = acc[ai][bj][m][0], a1 = acc[ai][bj][m][1]; if constexpr (GN) { a0 *= rc[ai * 4 + m]; a1 *= rc[ai * 4 + m]; }
;                     const f32x4 o0 = b0 + g[bj][0] * a0, o1 = b1 + g[bj][1] * a1;
;                     u32x4 wo; wo.x = cvt_pk_bf16(o0[0], o0[1]); wo.y = cvt_pk_bf16(o0[2], o0[3]); wo.z = cvt_pk_bf16(o1[0], o1[1]); wo.w = cvt_pk_bf16(o1[2], o1[3]);
;                     *(gs_u32x4*)(PG8_GPTR(out) + offb) = wo;
;                     if (xg) {
;                         const f32x4 h0 = o0 * cf[bj][0], h1 = o1 * cf[bj][1];
;                         u32x4 w; w.x = cvt_pk_bf16(h0[0], h0[1]); w.y = cvt_pk_bf16(h0[2], h0[3]); w.z = cvt_pk_bf16(h1[0], h1[1]); w.w = cvt_pk_bf16(h1[2], h1[3]);
;                         *(gs_u32x4*)(PG8_GPTR(xg) + offb) = w;
;                         q += (o0[0] * o0[0] + o0[1] * o0[1]) + (o0[2] * o0[2] + o0[3] * o0[3]) + (o1[0] * o1[0] + o1[1] * o1[1]) + (o1[2] * o1[2] + o1[3] * o1[3]);
;                     }
;                 }
;                 if (xg) ssq_put(ssq, row, q, fr, fq);
;             }
.LBB0_1263:
	v_lshlrev_b32_e32 v112, 16, v126
	v_and_b32_e32 v113, 0xffff0000, v126
	v_lshlrev_b32_e32 v114, 16, v127
	v_and_b32_e32 v115, 0xffff0000, v127
	v_lshlrev_b32_e32 v126, 16, v128
	v_and_b32_e32 v127, 0xffff0000, v128
	v_lshlrev_b32_e32 v128, 16, v129
	v_and_b32_e32 v129, 0xffff0000, v129
	v_lshl_add_u64 v[116:117], s[22:23], 0, v[130:131]
	v_pk_fma_f32 v[108:109], v[108:109], v[68:69], v[114:115]
	v_pk_fma_f32 v[106:107], v[106:107], v[66:67], v[112:113]
	v_pk_fma_f32 v[104:105], v[104:105], v[64:65], v[128:129]
	v_pk_fma_f32 v[102:103], v[102:103], v[62:63], v[126:127]
	s_and_b64 vcc, exec, s[8:9]
	v_cvt_pk_bf16_f32 v112, v106, v107
	v_cvt_pk_bf16_f32 v113, v108, v109
	v_cvt_pk_bf16_f32 v114, v102, v103
	v_cvt_pk_bf16_f32 v115, v104, v105
	global_store_dwordx4 v241, v[112:115], s[22:23] offset:1024 nt
	s_cbranch_vccnz .LBB0_1267
	s_nop 0
	v_pk_mul_f32 v[112:113], v[148:149], v[108:109]
	v_mul_f32_e32 v115, v107, v107
	v_mul_f32_e32 v109, v109, v109
	v_mul_f32_e32 v114, v103, v103
	v_fmac_f32_e32 v115, v106, v106
	v_fmac_f32_e32 v109, v108, v108
	v_mul_f32_e32 v111, v105, v105
	v_fmac_f32_e32 v114, v102, v102
	v_add_f32_e32 v108, v115, v109
	v_fmac_f32_e32 v111, v104, v104
	v_add_f32_e32 v108, v114, v108
	v_add_f32_e32 v108, v111, v108
	v_add_f32_e32 v114, v108, v110
	ds_bpermute_b32 v115, v159, v114
	v_pk_mul_f32 v[110:111], v[146:147], v[102:103]
	v_pk_mul_f32 v[106:107], v[142:143], v[106:107]
	v_pk_mul_f32 v[108:109], v[144:145], v[104:105]
	v_cvt_pk_bf16_f32 v104, v106, v107
	s_waitcnt lgkmcnt(0)
	v_add_f32_e32 v102, v114, v115
	ds_bpermute_b32 v103, v158, v102
	v_cvt_pk_bf16_f32 v105, v112, v113
	v_cvt_pk_bf16_f32 v106, v110, v111
	v_cvt_pk_bf16_f32 v107, v108, v109
	global_store_dwordx4 v[132:133], v[104:107], off offset:256
	s_and_saveexec_b64 s[2:3], s[10:11]
	s_cbranch_execz .LBB0_1266
	s_waitcnt lgkmcnt(0)
	v_add_f32_e32 v102, v102, v103
	v_mul_f32_e32 v102, 0x4b800000, v102
	v_trunc_f32_e32 v102, v102
	v_mul_f32_e32 v103, 0x2f800000, v102
	v_floor_f32_e32 v103, v103
	v_fmac_f32_e32 v102, 0xcf800000, v103
	v_cvt_u32_f32_e32 v102, v102
	v_cvt_u32_f32_e32 v103, v103
	v_ashrrev_i32_e32 v205, 31, v204
	v_lshl_add_u64 v[104:105], v[204:205], 3, s[16:17]
	global_atomic_add_x2 v[104:105], v[102:103], off offset:256

; __device__ __forceinline__ unsigned cvt_pk_bf16(float lo, float hi) { unsigned r; asm volatile("v_cvt_pk_bf16_f32 %0, %1, %2" : "=v"(r) : "v"(lo), "v"(hi)); return r; }
; #define PG8_GPTR(p) ((__attribute__((address_space(1))) char*)(p))
;     __device__ __forceinline__ void operator()(const f32x4 (&acc)[2][2][4][2], const Unit& u, int wr, int wc, int fr, int fq) const {
;     ...
;             for (int mm = 0; mm < 2; ++mm) {
;                 const int m = mp + mm;
;                 const int row = u.pm * BM + ai * HALF + wr * 64 + m * 16 + fr; float q = 0.f;
; #pragma unroll
;                 for (int bj = 0; bj < 2; ++bj) {
;                     const unsigned offb = (unsigned)(row * DM + col0 + bj * HALF) * 2u;
;                     const u32x4 bw = bv[mm][bj];
;                     const f32x4 b0 = (f32x4){__uint_as_float(bw.x << 16), __uint_as_float(bw.x & 0xffff0000u), __uint_as_float(bw.y << 16), __uint_as_float(bw.y & 0xffff0000u)};
;                     const f32x4 b1 = (f32x4){__uint_as_float(bw.z << 16), __uint_as_float(bw.z & 0xffff0000u), __uint_as_float(bw.w << 16), __uint_as_float(bw.w & 0xffff0000u)};
;                     f32x4 a0 = acc[ai][bj][m][0], a1 = acc[ai][bj][m][1]; if constexpr (GN) { a0 *= rc[ai * 4 + m]; a1 *= rc[ai * 4 + m]; }
;                     const f32x4 o0 = b0 + g[bj][0] * a0, o1 = b1 + g[bj][1] * a1;
;                     u32x4 wo; wo.x = cvt_pk_bf16(o0[0], o0[1]); wo.y = cvt_pk_bf16(o0[2], o0[3]); wo.z = cvt_pk_bf16(o1[0], o1[1]); wo.w = cvt_pk_bf16(o1[2], o1[3]);
;                     *(gs_u32x4*)(PG8_GPTR(out) + offb) = wo;
;                     if (xg) {
;                         const f32x4 h0 = o0 * cf[bj][0], h1 = o1 * cf[bj][1];
;                         u32x4 w; w.x = cvt_pk_bf16(h0[0], h0[1]); w.y = cvt_pk_bf16(h0[2], h0[3]); w.z = cvt_pk_bf16(h1[0], h1[1]); w.w = cvt_pk_bf16(h1[2], h1[3]);
;                         *(gs_u32x4*)(PG8_GPTR(xg) + offb) = w;
;                         q += (o0[0] * o0[0] + o0[1] * o0[1]) + (o0[2] * o0[2] + o0[3] * o0[3]) + (o1[0] * o1[0] + o1[1] * o1[1]) + (o1[2] * o1[2] + o1[3] * o1[3]);
;                     }
;                 }
;                 if (xg) ssq_put(ssq, row, q, fr, fq);
;             }
.LBB0_1267:
	s_mov_b32 s2, 0x18000
	v_add3_u32 v102, v217, v218, s2
	v_add_u32_e32 v241, s2, v240
	v_lshlrev_b32_e32 v104, 16, v122
	v_and_b32_e32 v105, 0xffff0000, v122
	v_lshlrev_b32_e32 v106, 16, v123
	v_and_b32_e32 v107, 0xffff0000, v123
	v_lshlrev_b32_e32 v108, 16, v124
	v_and_b32_e32 v109, 0xffff0000, v124
	v_lshlrev_b32_e32 v110, 16, v125
	v_and_b32_e32 v111, 0xffff0000, v125
	s_waitcnt lgkmcnt(0)
	v_mov_b32_e32 v103, v1
	v_pk_fma_f32 v[100:101], v[100:101], v[76:77], v[106:107]
	v_pk_fma_f32 v[98:99], v[98:99], v[74:75], v[104:105]
	v_pk_fma_f32 v[96:97], v[96:97], v[72:73], v[110:111]
	v_pk_fma_f32 v[104:105], v[94:95], v[70:71], v[108:109]
	s_and_b64 vcc, exec, s[8:9]
	v_lshl_add_u64 v[94:95], s[12:13], 0, v[102:103]
	v_cvt_pk_bf16_f32 v106, v98, v99
	v_cvt_pk_bf16_f32 v107, v100, v101
	v_cvt_pk_bf16_f32 v108, v104, v105
	v_cvt_pk_bf16_f32 v109, v96, v97
	global_store_dwordx4 v241, v[106:109], s[22:23] nt
	s_cbranch_vccnz .LBB0_1269
	s_nop 0
	v_pk_mul_f32 v[106:107], v[212:213], v[98:99]
	v_pk_mul_f32 v[108:109], v[210:211], v[100:101]
	v_cvt_pk_bf16_f32 v106, v106, v107
	v_pk_mul_f32 v[100:101], v[100:101], v[100:101]
	v_cvt_pk_bf16_f32 v107, v108, v109
	v_pk_mul_f32 v[98:99], v[98:99], v[98:99]
	v_pk_mul_f32 v[110:111], v[206:207], v[96:97]
	v_pk_mul_f32 v[112:113], v[208:209], v[104:105]
	v_pk_mul_f32 v[96:97], v[96:97], v[96:97]
	v_cvt_pk_bf16_f32 v108, v112, v113
	v_cvt_pk_bf16_f32 v109, v110, v111
	global_store_dwordx4 v[94:95], v[106:109], off
	s_nop 1
	v_mov_b32_e32 v106, v98
	v_mov_b32_e32 v107, v101
	v_pk_mov_b32 v[98:99], v[98:99], v[100:101] op_sel:[1,0]
	v_pk_mul_f32 v[100:101], v[104:105], v[104:105]
	v_pk_add_f32 v[98:99], v[98:99], v[106:107]
	v_mov_b32_e32 v104, v96
	v_mov_b32_e32 v105, v100
	v_mov_b32_e32 v100, v97
	v_pk_add_f32 v[96:97], v[104:105], v[100:101]
	v_add_f32_e32 v98, v98, v99
	v_add_f32_e32 v97, v97, v98
	v_add_f32_e32 v96, v96, v97
	s_branch .LBB0_1270

; __device__ __forceinline__ unsigned cvt_pk_bf16(float lo, float hi) { unsigned r; asm volatile("v_cvt_pk_bf16_f32 %0, %1, %2" : "=v"(r) : "v"(lo), "v"(hi)); return r; }
; #define PG8_GPTR(p) ((__attribute__((address_space(1))) char*)(p))
;     __device__ __forceinline__ void operator()(const f32x4 (&acc)[2][2][4][2], const Unit& u, int wr, int wc, int fr, int fq) const {
;     ...
;             for (int mm = 0; mm < 2; ++mm) {
;                 const int m = mp + mm;
;                 const int row = u.pm * BM + ai * HALF + wr * 64 + m * 16 + fr; float q = 0.f;
; #pragma unroll
;                 for (int bj = 0; bj < 2; ++bj) {
;                     const unsigned offb = (unsigned)(row * DM + col0 + bj * HALF) * 2u;
;                     const u32x4 bw = bv[mm][bj];
;                     const f32x4 b0 = (f32x4){__uint_as_float(bw.x << 16), __uint_as_float(bw.x & 0xffff0000u), __uint_as_float(bw.y << 16), __uint_as_float(bw.y & 0xffff0000u)};
;                     const f32x4 b1 = (f32x4){__uint_as_float(bw.z << 16), __uint_as_float(bw.z & 0xffff0000u), __uint_as_float(bw.w << 16), __uint_as_float(bw.w & 0xffff0000u)};
;                     f32x4 a0 = acc[ai][bj][m][0], a1 = acc[ai][bj][m][1]; if constexpr (GN) { a0 *= rc[ai * 4 + m]; a1 *= rc[ai * 4 + m]; }
;                     const f32x4 o0 = b0 + g[bj][0] * a0, o1 = b1 + g[bj][1] * a1;
;                     u32x4 wo; wo.x = cvt_pk_bf16(o0[0], o0[1]); wo.y = cvt_pk_bf16(o0[2], o0[3]); wo.z = cvt_pk_bf16(o1[0], o1[1]); wo.w = cvt_pk_bf16(o1[2], o1[3]);
;                     *(gs_u32x4*)(PG8_GPTR(out) + offb) = wo;
;                     if (xg) {
;                         const f32x4 h0 = o0 * cf[bj][0], h1 = o1 * cf[bj][1];
;                         u32x4 w; w.x = cvt_pk_bf16(h0[0], h0[1]); w.y = cvt_pk_bf16(h0[2], h0[3]); w.z = cvt_pk_bf16(h1[0], h1[1]); w.w = cvt_pk_bf16(h1[2], h1[3]);
;                         *(gs_u32x4*)(PG8_GPTR(xg) + offb) = w;
;                         q += (o0[0] * o0[0] + o0[1] * o0[1]) + (o0[2] * o0[2] + o0[3] * o0[3]) + (o1[0] * o1[0] + o1[1] * o1[1]) + (o1[2] * o1[2] + o1[3] * o1[3]);
;                     }
;                 }
;                 if (xg) ssq_put(ssq, row, q, fr, fq);
;             }
.LBB0_1270:
	v_lshlrev_b32_e32 v98, 16, v118
	v_and_b32_e32 v99, 0xffff0000, v118
	v_lshlrev_b32_e32 v100, 16, v119
	v_and_b32_e32 v101, 0xffff0000, v119
	v_lshlrev_b32_e32 v104, 16, v120
	v_and_b32_e32 v105, 0xffff0000, v120
	v_lshlrev_b32_e32 v106, 16, v121
	v_and_b32_e32 v107, 0xffff0000, v121
	v_lshl_add_u64 v[102:103], s[22:23], 0, v[102:103]
	v_pk_fma_f32 v[92:93], v[92:93], v[68:69], v[100:101]
	v_pk_fma_f32 v[90:91], v[90:91], v[66:67], v[98:99]
	v_pk_fma_f32 v[88:89], v[88:89], v[64:65], v[106:107]
	v_pk_fma_f32 v[86:87], v[86:87], v[62:63], v[104:105]
	s_and_b64 vcc, exec, s[8:9]
	v_cvt_pk_bf16_f32 v98, v90, v91
	v_cvt_pk_bf16_f32 v99, v92, v93
	v_cvt_pk_bf16_f32 v100, v86, v87
	v_cvt_pk_bf16_f32 v101, v88, v89
	global_store_dwordx4 v241, v[98:101], s[22:23] offset:1024 nt
	s_cbranch_vccnz .LBB0_1274
	s_nop 0
	v_pk_mul_f32 v[98:99], v[148:149], v[92:93]
	v_mul_f32_e32 v101, v91, v91
	v_mul_f32_e32 v93, v93, v93
	v_mul_f32_e32 v100, v87, v87
	v_fmac_f32_e32 v101, v90, v90
	v_fmac_f32_e32 v93, v92, v92
	v_mul_f32_e32 v97, v89, v89
	v_fmac_f32_e32 v100, v86, v86
	v_add_f32_e32 v92, v101, v93
	v_fmac_f32_e32 v97, v88, v88
	v_add_f32_e32 v92, v100, v92
	v_add_f32_e32 v92, v97, v92
	v_add_f32_e32 v100, v92, v96
	ds_bpermute_b32 v101, v159, v100
	v_pk_mul_f32 v[96:97], v[146:147], v[86:87]
	v_pk_mul_f32 v[90:91], v[142:143], v[90:91]
	v_pk_mul_f32 v[92:93], v[144:145], v[88:89]
	v_cvt_pk_bf16_f32 v88, v90, v91
	s_waitcnt lgkmcnt(0)
	v_add_f32_e32 v86, v100, v101
	ds_bpermute_b32 v87, v158, v86
	v_cvt_pk_bf16_f32 v89, v98, v99
	v_cvt_pk_bf16_f32 v90, v96, v97
	v_cvt_pk_bf16_f32 v91, v92, v93
	global_store_dwordx4 v[94:95], v[88:91], off offset:256
	s_and_saveexec_b64 s[2:3], s[10:11]
	s_cbranch_execz .LBB0_1273
	s_waitcnt lgkmcnt(0)
	v_add_f32_e32 v86, v86, v87
	v_mul_f32_e32 v86, 0x4b800000, v86
	v_trunc_f32_e32 v86, v86
	v_mul_f32_e32 v87, 0x2f800000, v86
	v_floor_f32_e32 v87, v87
	v_fmac_f32_e32 v86, 0xcf800000, v87
	v_cvt_u32_f32_e32 v86, v86
	v_cvt_u32_f32_e32 v87, v87
	v_ashrrev_i32_e32 v205, 31, v204
	v_lshl_add_u64 v[88:89], v[204:205], 3, s[16:17]
	global_atomic_add_x2 v[88:89], v[86:87], off offset:384

; #define PG8_GPTR(p) ((__attribute__((address_space(1))) char*)(p))
;     __device__ __forceinline__ void operator()(const f32x4 (&acc)[2][2][4][2], const Unit& u, int wr, int wc, int fr, int fq) const {
;     ...
;             u32x4 bv[2][2];
; #pragma unroll
;             for (int mm = 0; mm < 2; ++mm)
; #pragma unroll
;                 for (int bj = 0; bj < 2; ++bj)
;                     bv[mm][bj] = *(gl_u32x4*)(PG8_GCPTR(base) + (unsigned)((u.pm * BM + ai * HALF + wr * 64 + (mp + mm) * 16 + fr) * DM + col0 + bj * HALF) * 2u);
; #pragma unroll
;             for (int mm = 0; mm < 2; ++mm) {
;                 const int m = mp + mm;
;                 const int row = u.pm * BM + ai * HALF + wr * 64 + m * 16 + fr; float q = 0.f;
; #pragma unroll
;                 for (int bj = 0; bj < 2; ++bj) {
;                     const unsigned offb = (unsigned)(row * DM + col0 + bj * HALF) * 2u;
;                     const u32x4 bw = bv[mm][bj];
;                     const f32x4 b0 = (f32x4){__uint_as_float(bw.x << 16), __uint_as_float(bw.x & 0xffff0000u), __uint_as_float(bw.y << 16), __uint_as_float(bw.y & 0xffff0000u)};
;                     const f32x4 b1 = (f32x4){__uint_as_float(bw.z << 16), __uint_as_float(bw.z & 0xffff0000u), __uint_as_float(bw.w << 16), __uint_as_float(bw.w & 0xffff0000u)};
;                     f32x4 a0 = acc[ai][bj][m][0], a1 = acc[ai][bj][m][1]; if constexpr (GN) { a0 *= rc[ai * 4 + m]; a1 *= rc[ai * 4 + m]; }
;                     const f32x4 o0 = b0 + g[bj][0] * a0, o1 = b1 + g[bj][1] * a1;
;                     u32x4 wo; wo.x = cvt_pk_bf16(o0[0], o0[1]); wo.y = cvt_pk_bf16(o0[2], o0[3]); wo.z = cvt_pk_bf16(o1[0], o1[1]); wo.w = cvt_pk_bf16(o1[2], o1[3]);
;                     *(gs_u32x4*)(PG8_GPTR(out) + offb) = wo;
;                     if (xg) {
;                         const f32x4 h0 = o0 * cf[bj][0], h1 = o1 * cf[bj][1];
;                         u32x4 w; w.x = cvt_pk_bf16(h0[0], h0[1]); w.y = cvt_pk_bf16(h0[2], h0[3]); w.z = cvt_pk_bf16(h1[0], h1[1]); w.w = cvt_pk_bf16(h1[2], h1[3]);
;                         *(gs_u32x4*)(PG8_GPTR(xg) + offb) = w;
;                         q += (o0[0] * o0[0] + o0[1] * o0[1]) + (o0[2] * o0[2] + o0[3] * o0[3]) + (o1[0] * o1[0] + o1[1] * o1[1]) + (o1[2] * o1[2] + o1[3] * o1[3]);
;                     }
;                 }
;                 if (xg) ssq_put(ssq, row, q, fr, fq);
;             }
.LBB0_1274:
	v_add_u32_e32 v86, 0x40000, v240
	global_load_dwordx4 v[100:103], v86, s[20:21] nt
	global_load_dwordx4 v[94:97], v86, s[20:21] offset:1024 nt
	v_add_u32_e32 v86, 0x48000, v240
	global_load_dwordx4 v[90:93], v86, s[20:21] nt
	s_waitcnt lgkmcnt(0)
	global_load_dwordx4 v[86:89], v86, s[20:21] offset:1024 nt
	s_mov_b32 s2, 0x40000
	v_add3_u32 v98, v218, v217, s2
	v_add_u32_e32 v241, s2, v240
	v_mov_b32_e32 v99, v1
	s_and_b64 vcc, exec, s[8:9]
	s_waitcnt vmcnt(0)
	v_lshlrev_b32_e32 v104, 16, v100
	v_and_b32_e32 v105, 0xffff0000, v100
	v_lshlrev_b32_e32 v100, 16, v101
	v_and_b32_e32 v101, 0xffff0000, v101
	v_lshlrev_b32_e32 v106, 16, v102
	v_and_b32_e32 v107, 0xffff0000, v102
	v_lshlrev_b32_e32 v102, 16, v103
	v_and_b32_e32 v103, 0xffff0000, v103
	v_pk_fma_f32 v[84:85], v[84:85], v[76:77], v[100:101]
	v_pk_fma_f32 v[82:83], v[82:83], v[74:75], v[104:105]
	v_pk_fma_f32 v[80:81], v[80:81], v[72:73], v[102:103]
	v_cvt_pk_bf16_f32 v100, v82, v83
	v_cvt_pk_bf16_f32 v101, v84, v85
	v_pk_fma_f32 v[78:79], v[78:79], v[70:71], v[106:107]
	s_nop 0
	v_cvt_pk_bf16_f32 v102, v78, v79
	v_cvt_pk_bf16_f32 v103, v80, v81
	global_store_dwordx4 v241, v[100:103], s[22:23] nt
	s_nop 1
	v_lshl_add_u64 v[100:101], s[12:13], 0, v[98:99]
	s_cbranch_vccnz .LBB0_1276
	v_pk_mul_f32 v[102:103], v[212:213], v[82:83]
	v_pk_mul_f32 v[104:105], v[210:211], v[84:85]
	v_cvt_pk_bf16_f32 v102, v102, v103
	v_pk_mul_f32 v[84:85], v[84:85], v[84:85]
	v_cvt_pk_bf16_f32 v103, v104, v105
	v_pk_mul_f32 v[82:83], v[82:83], v[82:83]
	v_pk_mul_f32 v[106:107], v[206:207], v[80:81]
	v_pk_mul_f32 v[108:109], v[208:209], v[78:79]
	v_pk_mul_f32 v[80:81], v[80:81], v[80:81]
	v_cvt_pk_bf16_f32 v104, v108, v109
	v_cvt_pk_bf16_f32 v105, v106, v107
	global_store_dwordx4 v[100:101], v[102:105], off
	v_pk_mul_f32 v[78:79], v[78:79], v[78:79]
	s_nop 0
	v_mov_b32_e32 v102, v82
	v_mov_b32_e32 v103, v85
	v_pk_mov_b32 v[82:83], v[82:83], v[84:85] op_sel:[1,0]
	v_mov_b32_e32 v84, v80
	v_pk_add_f32 v[82:83], v[82:83], v[102:103]
	v_mov_b32_e32 v85, v78
	v_mov_b32_e32 v78, v81
	v_pk_add_f32 v[78:79], v[84:85], v[78:79]
	v_add_f32_e32 v80, v82, v83
	v_add_f32_e32 v79, v79, v80
	v_add_f32_e32 v78, v78, v79
	s_branch .LBB0_1277

; __device__ __forceinline__ unsigned cvt_pk_bf16(float lo, float hi) { unsigned r; asm volatile("v_cvt_pk_bf16_f32 %0, %1, %2" : "=v"(r) : "v"(lo), "v"(hi)); return r; }
; #define PG8_GPTR(p) ((__attribute__((address_space(1))) char*)(p))
;     __device__ __forceinline__ void operator()(const f32x4 (&acc)[2][2][4][2], const Unit& u, int wr, int wc, int fr, int fq) const {
;     ...
;             for (int mm = 0; mm < 2; ++mm) {
;                 const int m = mp + mm;
;                 const int row = u.pm * BM + ai * HALF + wr * 64 + m * 16 + fr; float q = 0.f;
; #pragma unroll
;                 for (int bj = 0; bj < 2; ++bj) {
;                     const unsigned offb = (unsigned)(row * DM + col0 + bj * HALF) * 2u;
;                     const u32x4 bw = bv[mm][bj];
;                     const f32x4 b0 = (f32x4){__uint_as_float(bw.x << 16), __uint_as_float(bw.x & 0xffff0000u), __uint_as_float(bw.y << 16), __uint_as_float(bw.y & 0xffff0000u)};
;                     const f32x4 b1 = (f32x4){__uint_as_float(bw.z << 16), __uint_as_float(bw.z & 0xffff0000u), __uint_as_float(bw.w << 16), __uint_as_float(bw.w & 0xffff0000u)};
;                     f32x4 a0 = acc[ai][bj][m][0], a1 = acc[ai][bj][m][1]; if constexpr (GN) { a0 *= rc[ai * 4 + m]; a1 *= rc[ai * 4 + m]; }
;                     const f32x4 o0 = b0 + g[bj][0] * a0, o1 = b1 + g[bj][1] * a1;
;                     u32x4 wo; wo.x = cvt_pk_bf16(o0[0], o0[1]); wo.y = cvt_pk_bf16(o0[2], o0[3]); wo.z = cvt_pk_bf16(o1[0], o1[1]); wo.w = cvt_pk_bf16(o1[2], o1[3]);
;                     *(gs_u32x4*)(PG8_GPTR(out) + offb) = wo;
;                     if (xg) {
;                         const f32x4 h0 = o0 * cf[bj][0], h1 = o1 * cf[bj][1];
;                         u32x4 w; w.x = cvt_pk_bf16(h0[0], h0[1]); w.y = cvt_pk_bf16(h0[2], h0[3]); w.z = cvt_pk_bf16(h1[0], h1[1]); w.w = cvt_pk_bf16(h1[2], h1[3]);
;                         *(gs_u32x4*)(PG8_GPTR(xg) + offb) = w;
;                         q += (o0[0] * o0[0] + o0[1] * o0[1]) + (o0[2] * o0[2] + o0[3] * o0[3]) + (o1[0] * o1[0] + o1[1] * o1[1]) + (o1[2] * o1[2] + o1[3] * o1[3]);
;                     }
;                 }
;                 if (xg) ssq_put(ssq, row, q, fr, fq);
;             }
.LBB0_1277:
	v_lshlrev_b32_e32 v80, 16, v94
	v_and_b32_e32 v81, 0xffff0000, v94
	v_lshlrev_b32_e32 v82, 16, v95
	v_and_b32_e32 v83, 0xffff0000, v95
	v_lshlrev_b32_e32 v94, 16, v96
	v_and_b32_e32 v95, 0xffff0000, v96
	v_lshlrev_b32_e32 v96, 16, v97
	v_and_b32_e32 v97, 0xffff0000, v97
	v_lshl_add_u64 v[84:85], s[22:23], 0, v[98:99]
	v_pk_fma_f32 v[60:61], v[60:61], v[68:69], v[82:83]
	v_pk_fma_f32 v[58:59], v[58:59], v[66:67], v[80:81]
	v_pk_fma_f32 v[56:57], v[56:57], v[64:65], v[96:97]
	v_pk_fma_f32 v[54:55], v[54:55], v[62:63], v[94:95]
	s_and_b64 vcc, exec, s[8:9]
	v_cvt_pk_bf16_f32 v80, v58, v59
	v_cvt_pk_bf16_f32 v81, v60, v61
	v_cvt_pk_bf16_f32 v82, v54, v55
	v_cvt_pk_bf16_f32 v83, v56, v57
	global_store_dwordx4 v241, v[80:83], s[22:23] offset:1024 nt
	s_cbranch_vccnz .LBB0_1281
	s_nop 0
	v_pk_mul_f32 v[80:81], v[148:149], v[60:61]
	v_mul_f32_e32 v83, v59, v59
	v_mul_f32_e32 v61, v61, v61
	v_mul_f32_e32 v82, v55, v55
	v_fmac_f32_e32 v83, v58, v58
	v_fmac_f32_e32 v61, v60, v60
	v_mul_f32_e32 v79, v57, v57
	v_fmac_f32_e32 v82, v54, v54
	v_add_f32_e32 v60, v83, v61
	v_fmac_f32_e32 v79, v56, v56
	v_add_f32_e32 v60, v82, v60
	v_add_f32_e32 v60, v79, v60
	v_add_f32_e32 v82, v60, v78
	ds_bpermute_b32 v83, v159, v82
	v_pk_mul_f32 v[78:79], v[146:147], v[54:55]
	v_pk_mul_f32 v[58:59], v[142:143], v[58:59]
	v_pk_mul_f32 v[60:61], v[144:145], v[56:57]
	v_cvt_pk_bf16_f32 v56, v58, v59
	s_waitcnt lgkmcnt(0)
	v_add_f32_e32 v54, v82, v83
	ds_bpermute_b32 v55, v158, v54
	v_cvt_pk_bf16_f32 v57, v80, v81
	v_cvt_pk_bf16_f32 v58, v78, v79
	v_cvt_pk_bf16_f32 v59, v60, v61
	global_store_dwordx4 v[100:101], v[56:59], off offset:256
	s_and_saveexec_b64 s[2:3], s[10:11]
	s_cbranch_execz .LBB0_1280
	s_waitcnt lgkmcnt(0)
	v_add_f32_e32 v54, v54, v55
	v_mul_f32_e32 v54, 0x4b800000, v54
	v_trunc_f32_e32 v54, v54
	v_mul_f32_e32 v55, 0x2f800000, v54
	v_floor_f32_e32 v55, v55
	v_fmac_f32_e32 v54, 0xcf800000, v55
	v_cvt_u32_f32_e32 v54, v54
	v_cvt_u32_f32_e32 v55, v55
	v_ashrrev_i32_e32 v205, 31, v204
	v_lshl_add_u64 v[56:57], v[204:205], 3, s[16:17]
	global_atomic_add_x2 v[56:57], v[54:55], off offset:1024

; __device__ __forceinline__ unsigned cvt_pk_bf16(float lo, float hi) { unsigned r; asm volatile("v_cvt_pk_bf16_f32 %0, %1, %2" : "=v"(r) : "v"(lo), "v"(hi)); return r; }
; #define PG8_GPTR(p) ((__attribute__((address_space(1))) char*)(p))
;     __device__ __forceinline__ void operator()(const f32x4 (&acc)[2][2][4][2], const Unit& u, int wr, int wc, int fr, int fq) const {
;     ...
;             for (int mm = 0; mm < 2; ++mm) {
;                 const int m = mp + mm;
;                 const int row = u.pm * BM + ai * HALF + wr * 64 + m * 16 + fr; float q = 0.f;
; #pragma unroll
;                 for (int bj = 0; bj < 2; ++bj) {
;                     const unsigned offb = (unsigned)(row * DM + col0 + bj * HALF) * 2u;
;                     const u32x4 bw = bv[mm][bj];
;                     const f32x4 b0 = (f32x4){__uint_as_float(bw.x << 16), __uint_as_float(bw.x & 0xffff0000u), __uint_as_float(bw.y << 16), __uint_as_float(bw.y & 0xffff0000u)};
;                     const f32x4 b1 = (f32x4){__uint_as_float(bw.z << 16), __uint_as_float(bw.z & 0xffff0000u), __uint_as_float(bw.w << 16), __uint_as_float(bw.w & 0xffff0000u)};
;                     f32x4 a0 = acc[ai][bj][m][0], a1 = acc[ai][bj][m][1]; if constexpr (GN) { a0 *= rc[ai * 4 + m]; a1 *= rc[ai * 4 + m]; }
;                     const f32x4 o0 = b0 + g[bj][0] * a0, o1 = b1 + g[bj][1] * a1;
;                     u32x4 wo; wo.x = cvt_pk_bf16(o0[0], o0[1]); wo.y = cvt_pk_bf16(o0[2], o0[3]); wo.z = cvt_pk_bf16(o1[0], o1[1]); wo.w = cvt_pk_bf16(o1[2], o1[3]);
;                     *(gs_u32x4*)(PG8_GPTR(out) + offb) = wo;
;                     if (xg) {
;                         const f32x4 h0 = o0 * cf[bj][0], h1 = o1 * cf[bj][1];
;                         u32x4 w; w.x = cvt_pk_bf16(h0[0], h0[1]); w.y = cvt_pk_bf16(h0[2], h0[3]); w.z = cvt_pk_bf16(h1[0], h1[1]); w.w = cvt_pk_bf16(h1[2], h1[3]);
;                         *(gs_u32x4*)(PG8_GPTR(xg) + offb) = w;
;                         q += (o0[0] * o0[0] + o0[1] * o0[1]) + (o0[2] * o0[2] + o0[3] * o0[3]) + (o1[0] * o1[0] + o1[1] * o1[1]) + (o1[2] * o1[2] + o1[3] * o1[3]);
;                     }
;                 }
;                 if (xg) ssq_put(ssq, row, q, fr, fq);
;             }
.LBB0_1281:
	s_mov_b32 s2, 0x48000
	v_add3_u32 v54, v218, v217, s2
	v_add_u32_e32 v241, s2, v240
	v_lshlrev_b32_e32 v56, 16, v90
	v_and_b32_e32 v57, 0xffff0000, v90
	v_lshlrev_b32_e32 v58, 16, v91
	v_and_b32_e32 v59, 0xffff0000, v91
	v_lshlrev_b32_e32 v60, 16, v92
	v_and_b32_e32 v61, 0xffff0000, v92
	v_lshlrev_b32_e32 v78, 16, v93
	v_and_b32_e32 v79, 0xffff0000, v93
	s_waitcnt lgkmcnt(0)
	v_mov_b32_e32 v55, v1
	v_pk_fma_f32 v[52:53], v[52:53], v[76:77], v[58:59]
	v_pk_fma_f32 v[50:51], v[50:51], v[74:75], v[56:57]
	v_pk_fma_f32 v[48:49], v[48:49], v[72:73], v[78:79]
	v_pk_fma_f32 v[56:57], v[46:47], v[70:71], v[60:61]
	s_and_b64 vcc, exec, s[8:9]
	v_lshl_add_u64 v[46:47], s[12:13], 0, v[54:55]
	v_cvt_pk_bf16_f32 v58, v50, v51
	v_cvt_pk_bf16_f32 v59, v52, v53
	v_cvt_pk_bf16_f32 v60, v56, v57
	v_cvt_pk_bf16_f32 v61, v48, v49
	global_store_dwordx4 v241, v[58:61], s[22:23] nt
	s_cbranch_vccnz .LBB0_1283
	s_nop 0
	v_pk_mul_f32 v[58:59], v[212:213], v[50:51]
	v_pk_mul_f32 v[60:61], v[210:211], v[52:53]
	v_cvt_pk_bf16_f32 v58, v58, v59
	v_pk_mul_f32 v[52:53], v[52:53], v[52:53]
	v_cvt_pk_bf16_f32 v59, v60, v61
	v_pk_mul_f32 v[50:51], v[50:51], v[50:51]
	v_pk_mul_f32 v[78:79], v[206:207], v[48:49]
	v_pk_mul_f32 v[80:81], v[208:209], v[56:57]
	v_pk_mul_f32 v[48:49], v[48:49], v[48:49]
	v_cvt_pk_bf16_f32 v60, v80, v81
	v_cvt_pk_bf16_f32 v61, v78, v79
	global_store_dwordx4 v[46:47], v[58:61], off
	s_nop 1
	v_mov_b32_e32 v58, v50
	v_mov_b32_e32 v59, v53
	v_pk_mov_b32 v[50:51], v[50:51], v[52:53] op_sel:[1,0]
	v_pk_mul_f32 v[52:53], v[56:57], v[56:57]
	v_pk_add_f32 v[50:51], v[50:51], v[58:59]
	v_mov_b32_e32 v56, v48
	v_mov_b32_e32 v57, v52
	v_mov_b32_e32 v52, v49
	v_pk_add_f32 v[48:49], v[56:57], v[52:53]
	v_add_f32_e32 v50, v50, v51
	v_add_f32_e32 v49, v49, v50
	v_add_f32_e32 v48, v48, v49
	s_branch .LBB0_1284

; __device__ __forceinline__ unsigned cvt_pk_bf16(float lo, float hi) { unsigned r; asm volatile("v_cvt_pk_bf16_f32 %0, %1, %2" : "=v"(r) : "v"(lo), "v"(hi)); return r; }
; #define PG8_GPTR(p) ((__attribute__((address_space(1))) char*)(p))
;     __device__ __forceinline__ void operator()(const f32x4 (&acc)[2][2][4][2], const Unit& u, int wr, int wc, int fr, int fq) const {
;     ...
;             for (int mm = 0; mm < 2; ++mm) {
;                 const int m = mp + mm;
;                 const int row = u.pm * BM + ai * HALF + wr * 64 + m * 16 + fr; float q = 0.f;
; #pragma unroll
;                 for (int bj = 0; bj < 2; ++bj) {
;                     const unsigned offb = (unsigned)(row * DM + col0 + bj * HALF) * 2u;
;                     const u32x4 bw = bv[mm][bj];
;                     const f32x4 b0 = (f32x4){__uint_as_float(bw.x << 16), __uint_as_float(bw.x & 0xffff0000u), __uint_as_float(bw.y << 16), __uint_as_float(bw.y & 0xffff0000u)};
;                     const f32x4 b1 = (f32x4){__uint_as_float(bw.z << 16), __uint_as_float(bw.z & 0xffff0000u), __uint_as_float(bw.w << 16), __uint_as_float(bw.w & 0xffff0000u)};
;                     f32x4 a0 = acc[ai][bj][m][0], a1 = acc[ai][bj][m][1]; if constexpr (GN) { a0 *= rc[ai * 4 + m]; a1 *= rc[ai * 4 + m]; }
;                     const f32x4 o0 = b0 + g[bj][0] * a0, o1 = b1 + g[bj][1] * a1;
;                     u32x4 wo; wo.x = cvt_pk_bf16(o0[0], o0[1]); wo.y = cvt_pk_bf16(o0[2], o0[3]); wo.z = cvt_pk_bf16(o1[0], o1[1]); wo.w = cvt_pk_bf16(o1[2], o1[3]);
;                     *(gs_u32x4*)(PG8_GPTR(out) + offb) = wo;
;                     if (xg) {
;                         const f32x4 h0 = o0 * cf[bj][0], h1 = o1 * cf[bj][1];
;                         u32x4 w; w.x = cvt_pk_bf16(h0[0], h0[1]); w.y = cvt_pk_bf16(h0[2], h0[3]); w.z = cvt_pk_bf16(h1[0], h1[1]); w.w = cvt_pk_bf16(h1[2], h1[3]);
;                         *(gs_u32x4*)(PG8_GPTR(xg) + offb) = w;
;                         q += (o0[0] * o0[0] + o0[1] * o0[1]) + (o0[2] * o0[2] + o0[3] * o0[3]) + (o1[0] * o1[0] + o1[1] * o1[1]) + (o1[2] * o1[2] + o1[3] * o1[3]);
;                     }
;                 }
;                 if (xg) ssq_put(ssq, row, q, fr, fq);
;             }
.LBB0_1284:
	v_lshlrev_b32_e32 v50, 16, v86
	v_and_b32_e32 v51, 0xffff0000, v86
	v_lshlrev_b32_e32 v52, 16, v87
	v_and_b32_e32 v53, 0xffff0000, v87
	v_lshlrev_b32_e32 v56, 16, v88
	v_and_b32_e32 v57, 0xffff0000, v88
	v_lshlrev_b32_e32 v58, 16, v89
	v_and_b32_e32 v59, 0xffff0000, v89
	v_lshl_add_u64 v[54:55], s[22:23], 0, v[54:55]
	v_pk_fma_f32 v[44:45], v[44:45], v[68:69], v[52:53]
	v_pk_fma_f32 v[42:43], v[42:43], v[66:67], v[50:51]
	v_pk_fma_f32 v[40:41], v[40:41], v[64:65], v[58:59]
	v_pk_fma_f32 v[38:39], v[38:39], v[62:63], v[56:57]
	s_and_b64 vcc, exec, s[8:9]
	v_cvt_pk_bf16_f32 v50, v42, v43
	v_cvt_pk_bf16_f32 v51, v44, v45
	v_cvt_pk_bf16_f32 v52, v38, v39
	v_cvt_pk_bf16_f32 v53, v40, v41
	global_store_dwordx4 v241, v[50:53], s[22:23] offset:1024 nt
	s_cbranch_vccnz .LBB0_1288
	s_nop 0
	v_pk_mul_f32 v[50:51], v[148:149], v[44:45]
	v_mul_f32_e32 v53, v43, v43
	v_mul_f32_e32 v45, v45, v45
	v_mul_f32_e32 v52, v39, v39
	v_fmac_f32_e32 v53, v42, v42
	v_fmac_f32_e32 v45, v44, v44
	v_mul_f32_e32 v49, v41, v41
	v_fmac_f32_e32 v52, v38, v38
	v_add_f32_e32 v44, v53, v45
	v_fmac_f32_e32 v49, v40, v40
	v_add_f32_e32 v44, v52, v44
	v_add_f32_e32 v44, v49, v44
	v_add_f32_e32 v52, v44, v48
	ds_bpermute_b32 v53, v159, v52
	v_pk_mul_f32 v[48:49], v[146:147], v[38:39]
	v_pk_mul_f32 v[42:43], v[142:143], v[42:43]
	v_pk_mul_f32 v[44:45], v[144:145], v[40:41]
	v_cvt_pk_bf16_f32 v40, v42, v43
	s_waitcnt lgkmcnt(0)
	v_add_f32_e32 v38, v52, v53
	ds_bpermute_b32 v39, v158, v38
	v_cvt_pk_bf16_f32 v41, v50, v51
	v_cvt_pk_bf16_f32 v42, v48, v49
	v_cvt_pk_bf16_f32 v43, v44, v45
	global_store_dwordx4 v[46:47], v[40:43], off offset:256
	s_and_saveexec_b64 s[2:3], s[10:11]
	s_cbranch_execz .LBB0_1287
	s_waitcnt lgkmcnt(0)
	v_add_f32_e32 v38, v38, v39
	v_mul_f32_e32 v38, 0x4b800000, v38
	v_trunc_f32_e32 v38, v38
	v_mul_f32_e32 v39, 0x2f800000, v38
	v_floor_f32_e32 v39, v39
	v_fmac_f32_e32 v38, 0xcf800000, v39
	v_cvt_u32_f32_e32 v38, v38
	v_cvt_u32_f32_e32 v39, v39
	v_ashrrev_i32_e32 v205, 31, v204
	v_lshl_add_u64 v[40:41], v[204:205], 3, s[16:17]
	global_atomic_add_x2 v[40:41], v[38:39], off offset:1152

; #define PG8_GPTR(p) ((__attribute__((address_space(1))) char*)(p))
;     __device__ __forceinline__ void operator()(const f32x4 (&acc)[2][2][4][2], const Unit& u, int wr, int wc, int fr, int fq) const {
;     ...
;             u32x4 bv[2][2];
; #pragma unroll
;             for (int mm = 0; mm < 2; ++mm)
; #pragma unroll
;                 for (int bj = 0; bj < 2; ++bj)
;                     bv[mm][bj] = *(gl_u32x4*)(PG8_GCPTR(base) + (unsigned)((u.pm * BM + ai * HALF + wr * 64 + (mp + mm) * 16 + fr) * DM + col0 + bj * HALF) * 2u);
; #pragma unroll
;             for (int mm = 0; mm < 2; ++mm) {
;                 const int m = mp + mm;
;                 const int row = u.pm * BM + ai * HALF + wr * 64 + m * 16 + fr; float q = 0.f;
; #pragma unroll
;                 for (int bj = 0; bj < 2; ++bj) {
;                     const unsigned offb = (unsigned)(row * DM + col0 + bj * HALF) * 2u;
;                     const u32x4 bw = bv[mm][bj];
;                     const f32x4 b0 = (f32x4){__uint_as_float(bw.x << 16), __uint_as_float(bw.x & 0xffff0000u), __uint_as_float(bw.y << 16), __uint_as_float(bw.y & 0xffff0000u)};
;                     const f32x4 b1 = (f32x4){__uint_as_float(bw.z << 16), __uint_as_float(bw.z & 0xffff0000u), __uint_as_float(bw.w << 16), __uint_as_float(bw.w & 0xffff0000u)};
;                     f32x4 a0 = acc[ai][bj][m][0], a1 = acc[ai][bj][m][1]; if constexpr (GN) { a0 *= rc[ai * 4 + m]; a1 *= rc[ai * 4 + m]; }
;                     const f32x4 o0 = b0 + g[bj][0] * a0, o1 = b1 + g[bj][1] * a1;
;                     u32x4 wo; wo.x = cvt_pk_bf16(o0[0], o0[1]); wo.y = cvt_pk_bf16(o0[2], o0[3]); wo.z = cvt_pk_bf16(o1[0], o1[1]); wo.w = cvt_pk_bf16(o1[2], o1[3]);
;                     *(gs_u32x4*)(PG8_GPTR(out) + offb) = wo;
;                     if (xg) {
;                         const f32x4 h0 = o0 * cf[bj][0], h1 = o1 * cf[bj][1];
;                         u32x4 w; w.x = cvt_pk_bf16(h0[0], h0[1]); w.y = cvt_pk_bf16(h0[2], h0[3]); w.z = cvt_pk_bf16(h1[0], h1[1]); w.w = cvt_pk_bf16(h1[2], h1[3]);
;                         *(gs_u32x4*)(PG8_GPTR(xg) + offb) = w;
;                         q += (o0[0] * o0[0] + o0[1] * o0[1]) + (o0[2] * o0[2] + o0[3] * o0[3]) + (o1[0] * o1[0] + o1[1] * o1[1]) + (o1[2] * o1[2] + o1[3] * o1[3]);
;                     }
;                 }
;                 if (xg) ssq_put(ssq, row, q, fr, fq);
;             }
.LBB0_1288:
	v_add_u32_e32 v38, 0x50000, v240
	global_load_dwordx4 v[50:53], v38, s[20:21] nt
	v_add_u32_e32 v0, 0x58000, v240
	global_load_dwordx4 v[46:49], v38, s[20:21] offset:1024 nt
	global_load_dwordx4 v[42:45], v0, s[20:21] nt
	s_waitcnt lgkmcnt(0)
	global_load_dwordx4 v[38:41], v0, s[20:21] offset:1024 nt
	s_mov_b32 s2, 0x50000
	v_add3_u32 v0, v218, v217, s2
	v_add_u32_e32 v241, s2, v240
	s_and_b64 vcc, exec, s[8:9]
	s_waitcnt vmcnt(0)
	v_lshlrev_b32_e32 v54, 16, v50
	v_and_b32_e32 v55, 0xffff0000, v50
	v_lshlrev_b32_e32 v50, 16, v51
	v_and_b32_e32 v51, 0xffff0000, v51
	v_lshlrev_b32_e32 v56, 16, v52
	v_and_b32_e32 v57, 0xffff0000, v52
	v_lshlrev_b32_e32 v52, 16, v53
	v_and_b32_e32 v53, 0xffff0000, v53
	v_pk_fma_f32 v[36:37], v[36:37], v[76:77], v[50:51]
	v_pk_fma_f32 v[50:51], v[34:35], v[74:75], v[54:55]
	v_pk_fma_f32 v[32:33], v[32:33], v[72:73], v[52:53]
	v_pk_fma_f32 v[34:35], v[30:31], v[70:71], v[56:57]
	v_lshl_add_u64 v[30:31], s[12:13], 0, v[0:1]
	v_cvt_pk_bf16_f32 v52, v50, v51
	v_cvt_pk_bf16_f32 v53, v36, v37
	v_cvt_pk_bf16_f32 v54, v34, v35
	v_cvt_pk_bf16_f32 v55, v32, v33
	global_store_dwordx4 v241, v[52:55], s[22:23] nt
	s_cbranch_vccnz .LBB0_1290
	s_nop 0
	v_pk_mul_f32 v[52:53], v[212:213], v[50:51]
	v_pk_mul_f32 v[54:55], v[210:211], v[36:37]
	v_cvt_pk_bf16_f32 v52, v52, v53
	v_pk_mul_f32 v[36:37], v[36:37], v[36:37]
	v_cvt_pk_bf16_f32 v53, v54, v55
	v_pk_mul_f32 v[50:51], v[50:51], v[50:51]
	v_pk_mul_f32 v[56:57], v[206:207], v[32:33]
	v_pk_mul_f32 v[58:59], v[208:209], v[34:35]
	v_pk_mul_f32 v[32:33], v[32:33], v[32:33]
	v_cvt_pk_bf16_f32 v54, v58, v59
	v_cvt_pk_bf16_f32 v55, v56, v57
	global_store_dwordx4 v[30:31], v[52:55], off
	v_pk_mul_f32 v[34:35], v[34:35], v[34:35]
	s_nop 0
	v_mov_b32_e32 v52, v50
	v_mov_b32_e32 v53, v37
	v_pk_mov_b32 v[36:37], v[50:51], v[36:37] op_sel:[1,0]
	v_mov_b32_e32 v50, v32
	v_pk_add_f32 v[36:37], v[36:37], v[52:53]
	v_mov_b32_e32 v51, v34
	v_mov_b32_e32 v34, v33
	v_pk_add_f32 v[32:33], v[50:51], v[34:35]
	v_add_f32_e32 v34, v36, v37
	v_add_f32_e32 v33, v33, v34
	v_add_f32_e32 v32, v32, v33
	s_branch .LBB0_1291

; __device__ __forceinline__ unsigned cvt_pk_bf16(float lo, float hi) { unsigned r; asm volatile("v_cvt_pk_bf16_f32 %0, %1, %2" : "=v"(r) : "v"(lo), "v"(hi)); return r; }
; #define PG8_GPTR(p) ((__attribute__((address_space(1))) char*)(p))
;     __device__ __forceinline__ void operator()(const f32x4 (&acc)[2][2][4][2], const Unit& u, int wr, int wc, int fr, int fq) const {
;     ...
;             for (int mm = 0; mm < 2; ++mm) {
;                 const int m = mp + mm;
;                 const int row = u.pm * BM + ai * HALF + wr * 64 + m * 16 + fr; float q = 0.f;
; #pragma unroll
;                 for (int bj = 0; bj < 2; ++bj) {
;                     const unsigned offb = (unsigned)(row * DM + col0 + bj * HALF) * 2u;
;                     const u32x4 bw = bv[mm][bj];
;                     const f32x4 b0 = (f32x4){__uint_as_float(bw.x << 16), __uint_as_float(bw.x & 0xffff0000u), __uint_as_float(bw.y << 16), __uint_as_float(bw.y & 0xffff0000u)};
;                     const f32x4 b1 = (f32x4){__uint_as_float(bw.z << 16), __uint_as_float(bw.z & 0xffff0000u), __uint_as_float(bw.w << 16), __uint_as_float(bw.w & 0xffff0000u)};
;                     f32x4 a0 = acc[ai][bj][m][0], a1 = acc[ai][bj][m][1]; if constexpr (GN) { a0 *= rc[ai * 4 + m]; a1 *= rc[ai * 4 + m]; }
;                     const f32x4 o0 = b0 + g[bj][0] * a0, o1 = b1 + g[bj][1] * a1;
;                     u32x4 wo; wo.x = cvt_pk_bf16(o0[0], o0[1]); wo.y = cvt_pk_bf16(o0[2], o0[3]); wo.z = cvt_pk_bf16(o1[0], o1[1]); wo.w = cvt_pk_bf16(o1[2], o1[3]);
;                     *(gs_u32x4*)(PG8_GPTR(out) + offb) = wo;
;                     if (xg) {
;                         const f32x4 h0 = o0 * cf[bj][0], h1 = o1 * cf[bj][1];
;                         u32x4 w; w.x = cvt_pk_bf16(h0[0], h0[1]); w.y = cvt_pk_bf16(h0[2], h0[3]); w.z = cvt_pk_bf16(h1[0], h1[1]); w.w = cvt_pk_bf16(h1[2], h1[3]);
;                         *(gs_u32x4*)(PG8_GPTR(xg) + offb) = w;
;                         q += (o0[0] * o0[0] + o0[1] * o0[1]) + (o0[2] * o0[2] + o0[3] * o0[3]) + (o1[0] * o1[0] + o1[1] * o1[1]) + (o1[2] * o1[2] + o1[3] * o1[3]);
;                     }
;                 }
;                 if (xg) ssq_put(ssq, row, q, fr, fq);
;             }
.LBB0_1291:
	v_lshlrev_b32_e32 v34, 16, v46
	v_and_b32_e32 v35, 0xffff0000, v46
	v_lshlrev_b32_e32 v36, 16, v47
	v_and_b32_e32 v37, 0xffff0000, v47
	v_lshlrev_b32_e32 v46, 16, v48
	v_and_b32_e32 v47, 0xffff0000, v48
	v_lshlrev_b32_e32 v48, 16, v49
	v_and_b32_e32 v49, 0xffff0000, v49
	v_lshl_add_u64 v[50:51], s[22:23], 0, v[0:1]
	v_pk_fma_f32 v[28:29], v[28:29], v[68:69], v[36:37]
	v_pk_fma_f32 v[26:27], v[26:27], v[66:67], v[34:35]
	v_pk_fma_f32 v[24:25], v[24:25], v[64:65], v[48:49]
	v_pk_fma_f32 v[22:23], v[22:23], v[62:63], v[46:47]
	s_and_b64 vcc, exec, s[8:9]
	v_cvt_pk_bf16_f32 v34, v26, v27
	v_cvt_pk_bf16_f32 v35, v28, v29
	v_cvt_pk_bf16_f32 v36, v22, v23
	v_cvt_pk_bf16_f32 v37, v24, v25
	global_store_dwordx4 v241, v[34:37], s[22:23] offset:1024 nt
	s_cbranch_vccnz .LBB0_1295
	s_nop 0
	v_pk_mul_f32 v[34:35], v[148:149], v[28:29]
	v_mul_f32_e32 v36, v27, v27
	v_mul_f32_e32 v29, v29, v29
	v_mul_f32_e32 v33, v23, v23
	v_fmac_f32_e32 v36, v26, v26
	v_fmac_f32_e32 v29, v28, v28
	v_mul_f32_e32 v0, v25, v25
	v_fmac_f32_e32 v33, v22, v22
	v_add_f32_e32 v28, v36, v29
	v_fmac_f32_e32 v0, v24, v24
	v_add_f32_e32 v28, v33, v28
	v_add_f32_e32 v0, v0, v28
	v_add_f32_e32 v0, v0, v32
	ds_bpermute_b32 v36, v159, v0
	v_pk_mul_f32 v[32:33], v[146:147], v[22:23]
	v_pk_mul_f32 v[26:27], v[142:143], v[26:27]
	v_pk_mul_f32 v[28:29], v[144:145], v[24:25]
	v_cvt_pk_bf16_f32 v24, v26, v27
	s_waitcnt lgkmcnt(0)
	v_add_f32_e32 v0, v0, v36
	ds_bpermute_b32 v22, v158, v0
	v_cvt_pk_bf16_f32 v25, v34, v35
	v_cvt_pk_bf16_f32 v26, v32, v33
	v_cvt_pk_bf16_f32 v27, v28, v29
	global_store_dwordx4 v[30:31], v[24:27], off offset:256
	s_and_saveexec_b64 s[2:3], s[10:11]
	s_cbranch_execz .LBB0_1294
	s_waitcnt lgkmcnt(0)
	v_add_f32_e32 v0, v0, v22
	v_mul_f32_e32 v0, 0x4b800000, v0
	v_trunc_f32_e32 v0, v0
	v_mul_f32_e32 v22, 0x2f800000, v0
	v_floor_f32_e32 v23, v22
	v_fmac_f32_e32 v0, 0xcf800000, v23
	v_cvt_u32_f32_e32 v22, v0
	v_cvt_u32_f32_e32 v23, v23
	v_ashrrev_i32_e32 v205, 31, v204
	v_lshl_add_u64 v[24:25], v[204:205], 3, s[16:17]
	global_atomic_add_x2 v[24:25], v[22:23], off offset:1280

; __device__ __forceinline__ unsigned cvt_pk_bf16(float lo, float hi) { unsigned r; asm volatile("v_cvt_pk_bf16_f32 %0, %1, %2" : "=v"(r) : "v"(lo), "v"(hi)); return r; }
; #define PG8_GPTR(p) ((__attribute__((address_space(1))) char*)(p))
;     __device__ __forceinline__ void operator()(const f32x4 (&acc)[2][2][4][2], const Unit& u, int wr, int wc, int fr, int fq) const {
;     ...
;             for (int mm = 0; mm < 2; ++mm) {
;                 const int m = mp + mm;
;                 const int row = u.pm * BM + ai * HALF + wr * 64 + m * 16 + fr; float q = 0.f;
; #pragma unroll
;                 for (int bj = 0; bj < 2; ++bj) {
;                     const unsigned offb = (unsigned)(row * DM + col0 + bj * HALF) * 2u;
;                     const u32x4 bw = bv[mm][bj];
;                     const f32x4 b0 = (f32x4){__uint_as_float(bw.x << 16), __uint_as_float(bw.x & 0xffff0000u), __uint_as_float(bw.y << 16), __uint_as_float(bw.y & 0xffff0000u)};
;                     const f32x4 b1 = (f32x4){__uint_as_float(bw.z << 16), __uint_as_float(bw.z & 0xffff0000u), __uint_as_float(bw.w << 16), __uint_as_float(bw.w & 0xffff0000u)};
;                     f32x4 a0 = acc[ai][bj][m][0], a1 = acc[ai][bj][m][1]; if constexpr (GN) { a0 *= rc[ai * 4 + m]; a1 *= rc[ai * 4 + m]; }
;                     const f32x4 o0 = b0 + g[bj][0] * a0, o1 = b1 + g[bj][1] * a1;
;                     u32x4 wo; wo.x = cvt_pk_bf16(o0[0], o0[1]); wo.y = cvt_pk_bf16(o0[2], o0[3]); wo.z = cvt_pk_bf16(o1[0], o1[1]); wo.w = cvt_pk_bf16(o1[2], o1[3]);
;                     *(gs_u32x4*)(PG8_GPTR(out) + offb) = wo;
;                     if (xg) {
;                         const f32x4 h0 = o0 * cf[bj][0], h1 = o1 * cf[bj][1];
;                         u32x4 w; w.x = cvt_pk_bf16(h0[0], h0[1]); w.y = cvt_pk_bf16(h0[2], h0[3]); w.z = cvt_pk_bf16(h1[0], h1[1]); w.w = cvt_pk_bf16(h1[2], h1[3]);
;                         *(gs_u32x4*)(PG8_GPTR(xg) + offb) = w;
;                         q += (o0[0] * o0[0] + o0[1] * o0[1]) + (o0[2] * o0[2] + o0[3] * o0[3]) + (o1[0] * o1[0] + o1[1] * o1[1]) + (o1[2] * o1[2] + o1[3] * o1[3]);
;                     }
;                 }
;                 if (xg) ssq_put(ssq, row, q, fr, fq);
;             }
.LBB0_1295:
	s_mov_b32 s2, 0x58000
	v_add3_u32 v0, v218, v217, s2
	v_add_u32_e32 v241, s2, v240
	s_waitcnt lgkmcnt(0)
	v_lshlrev_b32_e32 v22, 16, v42
	v_and_b32_e32 v23, 0xffff0000, v42
	v_lshlrev_b32_e32 v24, 16, v43
	v_and_b32_e32 v25, 0xffff0000, v43
	v_lshlrev_b32_e32 v26, 16, v44
	v_and_b32_e32 v27, 0xffff0000, v44
	v_lshlrev_b32_e32 v28, 16, v45
	v_and_b32_e32 v29, 0xffff0000, v45
	v_pk_fma_f32 v[20:21], v[20:21], v[76:77], v[24:25]
	v_pk_fma_f32 v[18:19], v[18:19], v[74:75], v[22:23]
	v_pk_fma_f32 v[12:13], v[12:13], v[72:73], v[28:29]
	v_pk_fma_f32 v[22:23], v[10:11], v[70:71], v[26:27]
	s_and_b64 vcc, exec, s[8:9]
	v_lshl_add_u64 v[10:11], s[12:13], 0, v[0:1]
	v_cvt_pk_bf16_f32 v24, v18, v19
	v_cvt_pk_bf16_f32 v25, v20, v21
	v_cvt_pk_bf16_f32 v26, v22, v23
	v_cvt_pk_bf16_f32 v27, v12, v13
	global_store_dwordx4 v241, v[24:27], s[22:23] nt
	s_cbranch_vccnz .LBB0_1297
	s_nop 0
	v_pk_mul_f32 v[24:25], v[212:213], v[18:19]
	v_pk_mul_f32 v[26:27], v[210:211], v[20:21]
	v_cvt_pk_bf16_f32 v24, v24, v25
	v_pk_mul_f32 v[20:21], v[20:21], v[20:21]
	v_cvt_pk_bf16_f32 v25, v26, v27
	v_pk_mul_f32 v[18:19], v[18:19], v[18:19]
	v_pk_mul_f32 v[28:29], v[206:207], v[12:13]
	v_pk_mul_f32 v[30:31], v[208:209], v[22:23]
	v_pk_mul_f32 v[12:13], v[12:13], v[12:13]
	v_cvt_pk_bf16_f32 v26, v30, v31
	v_cvt_pk_bf16_f32 v27, v28, v29
	global_store_dwordx4 v[10:11], v[24:27], off
	s_nop 1
	v_mov_b32_e32 v24, v18
	v_mov_b32_e32 v25, v21
	v_pk_mov_b32 v[18:19], v[18:19], v[20:21] op_sel:[1,0]
	v_pk_mul_f32 v[20:21], v[22:23], v[22:23]
	v_pk_add_f32 v[18:19], v[18:19], v[24:25]
	v_mov_b32_e32 v22, v12
	v_mov_b32_e32 v23, v20
	v_mov_b32_e32 v20, v13
	v_pk_add_f32 v[12:13], v[22:23], v[20:21]
	v_add_f32_e32 v18, v18, v19
	v_add_f32_e32 v13, v13, v18
	v_add_f32_e32 v12, v12, v13
	s_branch .LBB0_1298

; __device__ __forceinline__ unsigned cvt_pk_bf16(float lo, float hi) { unsigned r; asm volatile("v_cvt_pk_bf16_f32 %0, %1, %2" : "=v"(r) : "v"(lo), "v"(hi)); return r; }
; #define PG8_GPTR(p) ((__attribute__((address_space(1))) char*)(p))
;     __device__ __forceinline__ void operator()(const f32x4 (&acc)[2][2][4][2], const Unit& u, int wr, int wc, int fr, int fq) const {
;     ...
;             for (int mm = 0; mm < 2; ++mm) {
;                 const int m = mp + mm;
;                 const int row = u.pm * BM + ai * HALF + wr * 64 + m * 16 + fr; float q = 0.f;
; #pragma unroll
;                 for (int bj = 0; bj < 2; ++bj) {
;                     const unsigned offb = (unsigned)(row * DM + col0 + bj * HALF) * 2u;
;                     const u32x4 bw = bv[mm][bj];
;                     const f32x4 b0 = (f32x4){__uint_as_float(bw.x << 16), __uint_as_float(bw.x & 0xffff0000u), __uint_as_float(bw.y << 16), __uint_as_float(bw.y & 0xffff0000u)};
;                     const f32x4 b1 = (f32x4){__uint_as_float(bw.z << 16), __uint_as_float(bw.z & 0xffff0000u), __uint_as_float(bw.w << 16), __uint_as_float(bw.w & 0xffff0000u)};
;                     f32x4 a0 = acc[ai][bj][m][0], a1 = acc[ai][bj][m][1]; if constexpr (GN) { a0 *= rc[ai * 4 + m]; a1 *= rc[ai * 4 + m]; }
;                     const f32x4 o0 = b0 + g[bj][0] * a0, o1 = b1 + g[bj][1] * a1;
;                     u32x4 wo; wo.x = cvt_pk_bf16(o0[0], o0[1]); wo.y = cvt_pk_bf16(o0[2], o0[3]); wo.z = cvt_pk_bf16(o1[0], o1[1]); wo.w = cvt_pk_bf16(o1[2], o1[3]);
;                     *(gs_u32x4*)(PG8_GPTR(out) + offb) = wo;
;                     if (xg) {
;                         const f32x4 h0 = o0 * cf[bj][0], h1 = o1 * cf[bj][1];
;                         u32x4 w; w.x = cvt_pk_bf16(h0[0], h0[1]); w.y = cvt_pk_bf16(h0[2], h0[3]); w.z = cvt_pk_bf16(h1[0], h1[1]); w.w = cvt_pk_bf16(h1[2], h1[3]);
;                         *(gs_u32x4*)(PG8_GPTR(xg) + offb) = w;
;                         q += (o0[0] * o0[0] + o0[1] * o0[1]) + (o0[2] * o0[2] + o0[3] * o0[3]) + (o1[0] * o1[0] + o1[1] * o1[1]) + (o1[2] * o1[2] + o1[3] * o1[3]);
;                     }
;                 }
;                 if (xg) ssq_put(ssq, row, q, fr, fq);
;             }
.LBB0_1298:
	v_lshlrev_b32_e32 v18, 16, v38
	v_and_b32_e32 v19, 0xffff0000, v38
	v_lshlrev_b32_e32 v20, 16, v39
	v_and_b32_e32 v21, 0xffff0000, v39
	v_lshlrev_b32_e32 v24, 16, v40
	v_and_b32_e32 v25, 0xffff0000, v40
	v_lshlrev_b32_e32 v26, 16, v41
	v_and_b32_e32 v27, 0xffff0000, v41
	v_lshl_add_u64 v[22:23], s[22:23], 0, v[0:1]
	v_pk_fma_f32 v[8:9], v[8:9], v[68:69], v[20:21]
	v_pk_fma_f32 v[6:7], v[6:7], v[66:67], v[18:19]
	v_pk_fma_f32 v[4:5], v[4:5], v[64:65], v[26:27]
	v_pk_fma_f32 v[2:3], v[2:3], v[62:63], v[24:25]
	s_and_b64 vcc, exec, s[8:9]
	v_cvt_pk_bf16_f32 v18, v6, v7
	v_cvt_pk_bf16_f32 v19, v8, v9
	v_cvt_pk_bf16_f32 v20, v2, v3
	v_cvt_pk_bf16_f32 v21, v4, v5
	global_store_dwordx4 v241, v[18:21], s[22:23] offset:1024 nt
	s_cbranch_vccnz .LBB0_1302
	s_nop 0
	v_pk_mul_f32 v[18:19], v[148:149], v[8:9]
	v_mul_f32_e32 v20, v7, v7
	v_mul_f32_e32 v9, v9, v9
	v_mul_f32_e32 v13, v3, v3
	v_fmac_f32_e32 v20, v6, v6
	v_fmac_f32_e32 v9, v8, v8
	v_mul_f32_e32 v0, v5, v5
	v_fmac_f32_e32 v13, v2, v2
	v_add_f32_e32 v8, v20, v9
	v_fmac_f32_e32 v0, v4, v4
	v_add_f32_e32 v8, v13, v8
	v_add_f32_e32 v0, v0, v8
	v_add_f32_e32 v0, v0, v12
	ds_bpermute_b32 v20, v159, v0
	v_pk_mul_f32 v[12:13], v[146:147], v[2:3]
	v_pk_mul_f32 v[6:7], v[142:143], v[6:7]
	v_pk_mul_f32 v[8:9], v[144:145], v[4:5]
	v_cvt_pk_bf16_f32 v4, v6, v7
	s_waitcnt lgkmcnt(0)
	v_add_f32_e32 v0, v0, v20
	ds_bpermute_b32 v2, v158, v0
	v_cvt_pk_bf16_f32 v5, v18, v19
	v_cvt_pk_bf16_f32 v6, v12, v13
	v_cvt_pk_bf16_f32 v7, v8, v9
	global_store_dwordx4 v[10:11], v[4:7], off offset:256
	s_and_saveexec_b64 s[2:3], s[10:11]
	s_cbranch_execz .LBB0_1301
	s_waitcnt lgkmcnt(0)
	v_add_f32_e32 v0, v0, v2
	v_mul_f32_e32 v0, 0x4b800000, v0
	v_trunc_f32_e32 v0, v0
	v_mul_f32_e32 v2, 0x2f800000, v0
	v_floor_f32_e32 v3, v2
	v_fmac_f32_e32 v0, 0xcf800000, v3
	v_cvt_u32_f32_e32 v2, v0
	v_cvt_u32_f32_e32 v3, v3
	v_ashrrev_i32_e32 v205, 31, v204
	v_lshl_add_u64 v[4:5], v[204:205], 3, s[16:17]
	global_atomic_add_x2 v[4:5], v[2:3], off offset:1408
